# PH0 g_mix hoist + sample-panel fast epilogue + write-through sample hand-offs
# speedup vs baseline: 1.0903x; 1.0232x over previous
; __device__ __forceinline__ unsigned cvt_pk_bf16(float lo, float hi) { unsigned r; asm volatile("v_cvt_pk_bf16_f32 %0, %1, %2" : "=v"(r) : "v"(lo), "v"(hi)); return r; }
; __global__ void __launch_bounds__(512, 2) fwd_kernel(Args a) {
;     ...
;         auto xn_rows2 = [&](int m) {
;             v2u* o8 = (v2u*)(XN + (size_t)m * D) + lane;
;             if (m < MTOT) {
;                 const float* xr = m < MP ? x_p + (size_t)m * D : x_s + (size_t)(m - MP) * D;
;                 const f32x4* xr4 = (const f32x4*)xr + lane;
;                 f32x4 v[2][4]; float sq0 = 0.f, sq1 = 0.f;
; #pragma unroll
;                 for (int j = 0; j < 4; ++j) { v[0][j] = __builtin_nontemporal_load(xr4 + 64 * j); v[1][j] = __builtin_nontemporal_load(xr4 + 256 + 64 * j); }
; #pragma unroll
;                 for (int j = 0; j < 4; ++j) { sq0 += (v[0][j][0] * v[0][j][0] + v[0][j][1] * v[0][j][1]) + (v[0][j][2] * v[0][j][2] + v[0][j][3] * v[0][j][3]);
;                                               sq1 += (v[1][j][0] * v[1][j][0] + v[1][j][1] * v[1][j][1]) + (v[1][j][2] * v[1][j][2] + v[1][j][3] * v[1][j][3]); }
;                 const float ms0 = wave_sum(sq0) * (1.0f / D) + EPS, ms1 = wave_sum(sq1) * (1.0f / D) + EPS; const float rs0 = rsqrtf(ms0), rs1 = rsqrtf(ms1);
;                 if (lane == 0) { RINV[m] = sqrtf(ms0); RINV[m + 1] = sqrtf(ms1); }
; #pragma unroll
;                 for (int j = 0; j < 4; ++j) { const f32x4 gq = ((const f32x4*)g_mix)[lane + 64 * j]; const f32x4 y0 = v[0][j] * rs0 * gq, y1 = v[1][j] * rs1 * gq;
;                     v2u w; w.x = cvt_pk_bf16(y0[0], y0[1]); w.y = cvt_pk_bf16(y0[2], y0[3]); o8[64 * j] = w;
;                     v2u w1; w1.x = cvt_pk_bf16(y1[0], y1[1]); w1.y = cvt_pk_bf16(y1[2], y1[3]); o8[256 + 64 * j] = w1; }
.LBB0_36:
	s_cmpk_gt_i32 s78, 0x1fff
	v_mbcnt_lo_u32_b32 v155, -1, 0
	v_lshlrev_b32_e32 v156, 4, v154
	s_cbranch_scc1 .LBB0_41
	v_mbcnt_hi_u32_b32 v0, -1, v155
	v_and_b32_e32 v1, 64, v0
	v_add_u32_e32 v1, 64, v1
	v_xor_b32_e32 v2, 1, v0
	v_cmp_lt_i32_e32 vcc, v2, v1
	s_lshl_b32 s12, s78, 1
	s_waitcnt lgkmcnt(0)
	s_lshl_b32 s16, s28, 4
	v_cndmask_b32_e32 v2, v0, v2, vcc
	v_lshlrev_b32_e32 v39, 2, v2
	v_xor_b32_e32 v2, 2, v0
	v_cmp_lt_i32_e32 vcc, v2, v1
	s_ashr_i32 s13, s12, 31
	s_ashr_i32 s17, s16, 31
	v_cndmask_b32_e32 v2, v0, v2, vcc
	v_lshlrev_b32_e32 v42, 2, v2
	v_xor_b32_e32 v2, 4, v0
	v_cmp_lt_i32_e32 vcc, v2, v1
	s_lshl_b64 s[18:19], s[12:13], 2
	s_lshl_b64 s[20:21], s[16:17], 2
	v_cndmask_b32_e32 v2, v0, v2, vcc
	v_lshlrev_b32_e32 v43, 2, v2
	v_xor_b32_e32 v2, 8, v0
	v_cmp_lt_i32_e32 vcc, v2, v1
	s_lshl_b64 s[0:1], s[12:13], 12
	s_add_u32 s0, s24, s0
	v_cndmask_b32_e32 v2, v0, v2, vcc
	v_lshlrev_b32_e32 v44, 2, v2
	v_xor_b32_e32 v2, 16, v0
	v_cmp_lt_i32_e32 vcc, v2, v1
	v_mov_b32_e32 v157, 0
	s_addc_u32 s1, s25, s1
	v_cndmask_b32_e32 v2, v0, v2, vcc
	v_lshlrev_b32_e32 v45, 2, v2
	v_xor_b32_e32 v2, 32, v0
	v_cmp_lt_i32_e32 vcc, v2, v1
	v_lshl_add_u64 v[32:33], s[44:45], 0, v[156:157]
	s_lshl_b64 s[22:23], s[16:17], 12
	v_cndmask_b32_e32 v0, v0, v2, vcc
	v_lshlrev_b32_e32 v46, 2, v0
	v_lshl_add_u64 v[0:1], s[0:1], 0, v[156:157]
	s_mov_b64 s[0:1], 0x1000
	v_lshl_add_u64 v[34:35], v[0:1], 0, s[0:1]
	s_lshl_b64 s[0:1], s[12:13], 11
	v_cmp_ne_u32_e32 vcc, 0, v154
	v_lshl_or_b32 v36, v154, 3, s0
	v_mov_b32_e32 v37, s1
	s_lshl_b64 s[46:47], s[16:17], 11
	s_mov_b32 s38, 0x3a800000
	v_mov_b32_e32 v38, 0x358637bd
	s_mov_b32 s0, 0xf800000
	v_mov_b32_e32 v47, 0x260
	v_mov_b32_e32 v48, 0xe0c0000
	s_mov_b32 s1, 0x800000
	s_mov_b32 s4, 0x1b00000
	global_load_dwordx4 v[238:241], v[32:33], off
	global_load_dwordx4 v[242:245], v[32:33], off offset:1024
	global_load_dwordx4 v[246:249], v[32:33], off offset:2048
	global_load_dwordx4 v[250:253], v[32:33], off offset:3072
	s_branch .LBB0_39
.LBB0_38:
	s_or_b64 exec, exec, s[10:11]
	v_mul_f32_e32 v49, 0x4b800000, v41
	v_mul_f32_e32 v56, 0x4b800000, v40
	v_cmp_gt_f32_e64 s[6:7], s1, v41
	v_cmp_gt_f32_e64 s[8:9], s1, v40
	v_lshl_add_u64 v[54:55], s[14:15], 0, v[36:37]
	v_cndmask_b32_e64 v41, v41, v49, s[6:7]
	v_cndmask_b32_e64 v40, v40, v56, s[8:9]
	v_rsq_f32_e32 v49, v41
	v_rsq_f32_e32 v56, v40
	v_add_co_u32_e64 v40, s[10:11], s4, v54
	v_mul_f32_e32 v54, 0x45800000, v49
	s_nop 0
	v_addc_co_u32_e64 v41, s[10:11], 0, v55, s[10:11]
	v_mul_f32_e32 v55, 0x45800000, v56
	v_cndmask_b32_e64 v54, v49, v54, s[6:7]
	v_cndmask_b32_e64 v56, v56, v55, s[8:9]
	v_pk_mul_f32 v[28:29], v[28:29], v[56:57] op_sel_hi:[1,0]
	v_pk_mul_f32 v[24:25], v[24:25], v[54:55] op_sel_hi:[1,0]
	v_pk_mul_f32 v[30:31], v[30:31], v[56:57] op_sel_hi:[1,0]
	v_pk_mul_f32 v[26:27], v[26:27], v[54:55] op_sel_hi:[1,0]
	v_pk_mul_f32 v[20:21], v[20:21], v[56:57] op_sel_hi:[1,0]
	v_pk_mul_f32 v[16:17], v[16:17], v[54:55] op_sel_hi:[1,0]
	v_pk_mul_f32 v[22:23], v[22:23], v[56:57] op_sel_hi:[1,0]
	v_pk_mul_f32 v[18:19], v[18:19], v[54:55] op_sel_hi:[1,0]
	v_pk_mul_f32 v[12:13], v[12:13], v[56:57] op_sel_hi:[1,0]
	v_pk_mul_f32 v[8:9], v[8:9], v[54:55] op_sel_hi:[1,0]
	v_pk_mul_f32 v[14:15], v[14:15], v[56:57] op_sel_hi:[1,0]
	v_pk_mul_f32 v[10:11], v[10:11], v[54:55] op_sel_hi:[1,0]
	s_add_i32 s12, s12, s16
	s_add_u32 s18, s18, s20
	s_addc_u32 s19, s19, s21
	v_pk_mul_f32 v[4:5], v[4:5], v[56:57] op_sel_hi:[1,0]
	v_pk_mul_f32 v[0:1], v[0:1], v[54:55] op_sel_hi:[1,0]
	v_lshl_add_u64 v[34:35], v[34:35], 0, s[22:23]
	s_cmpk_gt_i32 s12, 0x3fff
	v_pk_mul_f32 v[6:7], v[6:7], v[56:57] op_sel_hi:[1,0]
	v_pk_mul_f32 v[2:3], v[2:3], v[54:55] op_sel_hi:[1,0]
	v_lshl_add_u64 v[36:37], v[36:37], 0, s[46:47]
	v_pk_mul_f32 v[28:29], v[28:29], v[238:239]
	v_pk_mul_f32 v[24:25], v[24:25], v[238:239]
	v_pk_mul_f32 v[30:31], v[30:31], v[240:241]
	v_pk_mul_f32 v[26:27], v[26:27], v[240:241]
	v_cvt_pk_bf16_f32 v28, v28, v29
	v_cvt_pk_bf16_f32 v29, v30, v31
	global_store_dwordx2 v[40:41], v[28:29], off
	v_cvt_pk_bf16_f32 v24, v24, v25
	v_cvt_pk_bf16_f32 v25, v26, v27
	global_store_dwordx2 v[40:41], v[24:25], off offset:2048
	v_pk_mul_f32 v[20:21], v[20:21], v[242:243]
	v_pk_mul_f32 v[16:17], v[16:17], v[242:243]
	v_pk_mul_f32 v[22:23], v[22:23], v[244:245]
	v_pk_mul_f32 v[18:19], v[18:19], v[244:245]
	v_cvt_pk_bf16_f32 v20, v20, v21
	v_cvt_pk_bf16_f32 v21, v22, v23
	global_store_dwordx2 v[40:41], v[20:21], off offset:512
	v_cvt_pk_bf16_f32 v16, v16, v17
	v_cvt_pk_bf16_f32 v17, v18, v19
	global_store_dwordx2 v[40:41], v[16:17], off offset:2560
	v_pk_mul_f32 v[12:13], v[12:13], v[246:247]
	v_pk_mul_f32 v[8:9], v[8:9], v[246:247]
	v_pk_mul_f32 v[14:15], v[14:15], v[248:249]
	v_pk_mul_f32 v[10:11], v[10:11], v[248:249]
	v_cvt_pk_bf16_f32 v12, v12, v13
	v_cvt_pk_bf16_f32 v13, v14, v15
	global_store_dwordx2 v[40:41], v[12:13], off offset:1024
	v_cvt_pk_bf16_f32 v8, v8, v9
	v_cvt_pk_bf16_f32 v9, v10, v11
	global_store_dwordx2 v[40:41], v[8:9], off offset:3072
	v_pk_mul_f32 v[4:5], v[4:5], v[250:251]
	v_pk_mul_f32 v[0:1], v[0:1], v[250:251]
	v_pk_mul_f32 v[6:7], v[6:7], v[252:253]
	v_pk_mul_f32 v[2:3], v[2:3], v[252:253]
	v_cvt_pk_bf16_f32 v4, v4, v5
	v_cvt_pk_bf16_f32 v5, v6, v7
	global_store_dwordx2 v[40:41], v[4:5], off offset:1536
	v_cvt_pk_bf16_f32 v0, v0, v1
	v_cvt_pk_bf16_f32 v1, v2, v3
	global_store_dwordx2 v[40:41], v[0:1], off offset:3584
	s_cbranch_scc1 .LBB0_41

; __device__ __forceinline__ unsigned cvt_pk_bf16(float lo, float hi) { unsigned r; asm volatile("v_cvt_pk_bf16_f32 %0, %1, %2" : "=v"(r) : "v"(lo), "v"(hi)); return r; }
; __device__ __forceinline__ float bf2f(unsigned b) { return __uint_as_float(b << 16); }
;     __device__ __forceinline__ void operator()(const f32x4 (&acc)[2][2][4][2], const Unit& u, int wr, int wc, int fr, int fq) const {
;     ...
;                     const int col0 = u.pn * 256 + bj * 128 + wc * 32 + fq * 8;
;                     f32x4 x0 = (f32x4){0.f, 0.f, 0.f, 0.f}, x1 = x0;
;                     if (recon) {
;                         const v4u xb = __builtin_nontemporal_load((const v4u*)(XN + (size_t)row * D + col0));
;                         x0 = (f32x4){bf2f(xb.x & 0xffffu), bf2f(xb.x >> 16), bf2f(xb.y & 0xffffu), bf2f(xb.y >> 16)} * gi[bj][0] * ri;
;                         x1 = (f32x4){bf2f(xb.z & 0xffffu), bf2f(xb.z >> 16), bf2f(xb.w & 0xffffu), bf2f(xb.w >> 16)} * gi[bj][1] * ri;
;                     } else if (valid) { x0 = *(const f32x4*)(xr + col0); x1 = *(const f32x4*)(xr + col0 + 4); }
;                     const f32x4 v0 = acc[ai][bj][m][0] + x0, v1 = acc[ai][bj][m][1] + x1;
;                     ss += (v0[0] * v0[0] + v0[1] * v0[1]) + (v0[2] * v0[2] + v0[3] * v0[3]) + (v1[0] * v1[0] + v1[1] * v1[1]) + (v1[2] * v1[2] + v1[3] * v1[3]);
;                     if (valid && row >= MP) { *(f32x4*)(out + (size_t)row * D + col0) = v0; *(f32x4*)(out + (size_t)row * D + col0 + 4) = v1; }
;                     v4u w; w.x = cvt_pk_bf16(v0[0], v0[1]); w.y = cvt_pk_bf16(v0[2], v0[3]); w.z = cvt_pk_bf16(v1[0], v1[1]); w.w = cvt_pk_bf16(v1[2], v1[3]);
;                     *(v4u*)(XMIDB + (size_t)row * D + col0) = w;
.LBB0_711:
	v_lshlrev_b32_e32 v144, 10, v162
	s_waitcnt vmcnt(0)
	v_pk_add_f32 v[126:127], v[126:127], v[134:135]
	v_pk_add_f32 v[124:125], v[124:125], v[132:133]
	v_pk_add_f32 v[122:123], v[122:123], v[130:131]
	v_pk_add_f32 v[120:121], v[120:121], v[128:129]
	s_andn2_b64 vcc, exec, s[56:57]
	v_lshl_add_u64 v[166:167], v[144:145], 2, s[16:17]
	s_cbranch_vccnz .LBB0_713
	v_lshl_add_u64 v[128:129], v[150:151], 2, v[166:167]
	global_store_dwordx4 v[128:129], v[124:127], off sc1
	global_store_dwordx4 v[128:129], v[120:123], off offset:16 sc1
.LBB0_713:
	v_lshlrev_b64 v[132:133], 11, v[162:163]
	v_lshl_add_u64 v[164:165], s[26:27], 0, v[132:133]
	v_cvt_pk_bf16_f32 v128, v124, v125
	v_cvt_pk_bf16_f32 v129, v126, v127
	v_cvt_pk_bf16_f32 v130, v120, v121
	v_cvt_pk_bf16_f32 v131, v122, v123
	v_lshl_add_u64 v[132:133], v[150:151], 1, v[164:165]
	global_store_dwordx4 v[132:133], v[128:131], off sc1
	v_mov_b32_e32 v132, 0
	v_mov_b32_e32 v133, 0
	v_mov_b32_e32 v134, 0
	v_mov_b32_e32 v135, 0
	v_mov_b32_e32 v128, 0
	v_mov_b32_e32 v129, 0
	v_mov_b32_e32 v130, 0
	v_mov_b32_e32 v131, 0
	s_and_saveexec_b64 s[56:57], s[12:13]
	s_cbranch_execz .LBB0_715
	v_lshl_add_u64 v[128:129], v[150:151], 2, v[160:161]
	global_load_dwordx4 v[132:135], v[128:129], off offset:512
	s_nop 0
	global_load_dwordx4 v[128:131], v[128:129], off offset:528

; __device__ __forceinline__ unsigned cvt_pk_bf16(float lo, float hi) { unsigned r; asm volatile("v_cvt_pk_bf16_f32 %0, %1, %2" : "=v"(r) : "v"(lo), "v"(hi)); return r; }
; __device__ __forceinline__ float bf2f(unsigned b) { return __uint_as_float(b << 16); }
;     __device__ __forceinline__ void operator()(const f32x4 (&acc)[2][2][4][2], const Unit& u, int wr, int wc, int fr, int fq) const {
;     ...
;                     const int col0 = u.pn * 256 + bj * 128 + wc * 32 + fq * 8;
;                     f32x4 x0 = (f32x4){0.f, 0.f, 0.f, 0.f}, x1 = x0;
;                     if (recon) {
;                         const v4u xb = __builtin_nontemporal_load((const v4u*)(XN + (size_t)row * D + col0));
;                         x0 = (f32x4){bf2f(xb.x & 0xffffu), bf2f(xb.x >> 16), bf2f(xb.y & 0xffffu), bf2f(xb.y >> 16)} * gi[bj][0] * ri;
;                         x1 = (f32x4){bf2f(xb.z & 0xffffu), bf2f(xb.z >> 16), bf2f(xb.w & 0xffffu), bf2f(xb.w >> 16)} * gi[bj][1] * ri;
;                     } else if (valid) { x0 = *(const f32x4*)(xr + col0); x1 = *(const f32x4*)(xr + col0 + 4); }
;                     const f32x4 v0 = acc[ai][bj][m][0] + x0, v1 = acc[ai][bj][m][1] + x1;
;                     ss += (v0[0] * v0[0] + v0[1] * v0[1]) + (v0[2] * v0[2] + v0[3] * v0[3]) + (v1[0] * v1[0] + v1[1] * v1[1]) + (v1[2] * v1[2] + v1[3] * v1[3]);
;                     if (valid && row >= MP) { *(f32x4*)(out + (size_t)row * D + col0) = v0; *(f32x4*)(out + (size_t)row * D + col0 + 4) = v1; }
;                     v4u w; w.x = cvt_pk_bf16(v0[0], v0[1]); w.y = cvt_pk_bf16(v0[2], v0[3]); w.z = cvt_pk_bf16(v1[0], v1[1]); w.w = cvt_pk_bf16(v1[2], v1[3]);
;                     *(v4u*)(XMIDB + (size_t)row * D + col0) = w;
;                 }
;                 ss += __shfl_xor(ss, 16); ss += __shfl_xor(ss, 32);
;                 if (fq == 0) atomicAdd(SS + row, ss);
.LBB0_717:
	s_waitcnt vmcnt(1)
	v_pk_add_f32 v[118:119], v[118:119], v[134:135]
	v_pk_add_f32 v[116:117], v[116:117], v[132:133]
	s_waitcnt vmcnt(0)
	v_pk_add_f32 v[114:115], v[114:115], v[130:131]
	s_andn2_b64 vcc, exec, s[56:57]
	v_pk_add_f32 v[112:113], v[112:113], v[128:129]
	s_cbranch_vccnz .LBB0_719
	v_lshl_add_u64 v[128:129], v[150:151], 2, v[166:167]
	global_store_dwordx4 v[128:129], v[116:119], off offset:512 sc1
	global_store_dwordx4 v[128:129], v[112:115], off offset:528 sc1
.LBB0_719:
	v_mul_f32_e32 v125, v125, v125
	v_fmac_f32_e32 v125, v124, v124
	v_mul_f32_e32 v124, v127, v127
	v_fmac_f32_e32 v124, v126, v126
	v_mul_f32_e32 v121, v121, v121
	v_add_f32_e32 v124, v125, v124
	v_fmac_f32_e32 v121, v120, v120
	v_add_f32_e32 v120, v124, v121
	v_mul_f32_e32 v121, v123, v123
	v_fmac_f32_e32 v121, v122, v122
	v_add_f32_e32 v120, v121, v120
	v_mul_f32_e32 v121, v117, v117
	v_mul_f32_e32 v122, v119, v119
	v_fmac_f32_e32 v121, v116, v116
	v_fmac_f32_e32 v122, v118, v118
	v_add_f32_e32 v121, v121, v122
	v_mul_f32_e32 v122, v113, v113
	v_fmac_f32_e32 v122, v112, v112
	v_add_f32_e32 v121, v121, v122
	v_mul_f32_e32 v122, v115, v115
	v_fmac_f32_e32 v122, v114, v114
	v_add_f32_e32 v121, v122, v121
	v_add_f32_e32 v122, v120, v121
	v_and_b32_e32 v121, 64, v175
	v_xor_b32_e32 v120, 16, v175
	v_add_u32_e32 v123, 64, v121
	v_cmp_lt_i32_e32 vcc, v120, v123
	s_nop 1
	v_cndmask_b32_e32 v120, v175, v120, vcc
	v_lshlrev_b32_e32 v128, 2, v120
	ds_bpermute_b32 v124, v128, v122
	v_cvt_pk_bf16_f32 v120, v116, v117
	v_xor_b32_e32 v117, 32, v175
	v_cmp_lt_i32_e32 vcc, v117, v123
	v_cvt_pk_bf16_f32 v121, v118, v119
	s_waitcnt lgkmcnt(0)
	v_add_f32_e32 v116, v122, v124
	v_cvt_pk_bf16_f32 v122, v112, v113
	v_lshl_add_u64 v[112:113], v[160:161], 1, v[164:165]
	v_cndmask_b32_e32 v117, v175, v117, vcc
	v_lshlrev_b32_e32 v129, 2, v117
	ds_bpermute_b32 v117, v129, v116
	v_cvt_pk_bf16_f32 v123, v114, v115
	global_store_dwordx4 v[112:113], v[120:123], off sc1
	s_and_saveexec_b64 s[14:15], s[10:11]
	s_cbranch_execz .LBB0_721
	v_lshl_add_u64 v[112:113], v[162:163], 2, s[40:41]
	s_waitcnt lgkmcnt(0)
	v_add_f32_e32 v114, v116, v117
	global_atomic_add_f32 v[112:113], v114, off

; __device__ __forceinline__ unsigned cvt_pk_bf16(float lo, float hi) { unsigned r; asm volatile("v_cvt_pk_bf16_f32 %0, %1, %2" : "=v"(r) : "v"(lo), "v"(hi)); return r; }
; __device__ __forceinline__ float bf2f(unsigned b) { return __uint_as_float(b << 16); }
;     __device__ __forceinline__ void operator()(const f32x4 (&acc)[2][2][4][2], const Unit& u, int wr, int wc, int fr, int fq) const {
;     ...
;                     const int col0 = u.pn * 256 + bj * 128 + wc * 32 + fq * 8;
;                     f32x4 x0 = (f32x4){0.f, 0.f, 0.f, 0.f}, x1 = x0;
;                     if (recon) {
;                         const v4u xb = __builtin_nontemporal_load((const v4u*)(XN + (size_t)row * D + col0));
;                         x0 = (f32x4){bf2f(xb.x & 0xffffu), bf2f(xb.x >> 16), bf2f(xb.y & 0xffffu), bf2f(xb.y >> 16)} * gi[bj][0] * ri;
;                         x1 = (f32x4){bf2f(xb.z & 0xffffu), bf2f(xb.z >> 16), bf2f(xb.w & 0xffffu), bf2f(xb.w >> 16)} * gi[bj][1] * ri;
;                     } else if (valid) { x0 = *(const f32x4*)(xr + col0); x1 = *(const f32x4*)(xr + col0 + 4); }
;                     const f32x4 v0 = acc[ai][bj][m][0] + x0, v1 = acc[ai][bj][m][1] + x1;
;                     ss += (v0[0] * v0[0] + v0[1] * v0[1]) + (v0[2] * v0[2] + v0[3] * v0[3]) + (v1[0] * v1[0] + v1[1] * v1[1]) + (v1[2] * v1[2] + v1[3] * v1[3]);
;                     if (valid && row >= MP) { *(f32x4*)(out + (size_t)row * D + col0) = v0; *(f32x4*)(out + (size_t)row * D + col0 + 4) = v1; }
;                     v4u w; w.x = cvt_pk_bf16(v0[0], v0[1]); w.y = cvt_pk_bf16(v0[2], v0[3]); w.z = cvt_pk_bf16(v1[0], v1[1]); w.w = cvt_pk_bf16(v1[2], v1[3]);
;                     *(v4u*)(XMIDB + (size_t)row * D + col0) = w;
.LBB0_725:
	v_lshlrev_b32_e32 v144, 10, v120
	s_waitcnt vmcnt(1)
	v_pk_add_f32 v[110:111], v[110:111], v[118:119]
	v_pk_add_f32 v[108:109], v[108:109], v[116:117]
	s_waitcnt vmcnt(0)
	v_pk_add_f32 v[106:107], v[106:107], v[114:115]
	v_pk_add_f32 v[104:105], v[104:105], v[112:113]
	s_andn2_b64 vcc, exec, s[56:57]
	v_lshl_add_u64 v[126:127], v[144:145], 2, s[16:17]
	s_cbranch_vccnz .LBB0_727
	v_lshl_add_u64 v[112:113], v[150:151], 2, v[126:127]
	global_store_dwordx4 v[112:113], v[108:111], off sc1
	global_store_dwordx4 v[112:113], v[104:107], off offset:16 sc1
.LBB0_727:
	v_lshlrev_b64 v[116:117], 11, v[120:121]
	v_lshl_add_u64 v[122:123], s[26:27], 0, v[116:117]
	v_cvt_pk_bf16_f32 v112, v108, v109
	v_cvt_pk_bf16_f32 v113, v110, v111
	v_cvt_pk_bf16_f32 v114, v104, v105
	v_cvt_pk_bf16_f32 v115, v106, v107
	v_lshl_add_u64 v[116:117], v[150:151], 1, v[122:123]
	global_store_dwordx4 v[116:117], v[112:115], off sc1
	v_mov_b32_e32 v116, 0
	v_mov_b32_e32 v117, 0
	v_mov_b32_e32 v118, 0
	v_mov_b32_e32 v119, 0
	v_mov_b32_e32 v112, 0
	v_mov_b32_e32 v113, 0
	v_mov_b32_e32 v114, 0
	v_mov_b32_e32 v115, 0
	s_and_saveexec_b64 s[56:57], s[14:15]
	s_cbranch_execz .LBB0_729
	v_lshl_add_u64 v[112:113], v[150:151], 2, v[124:125]
	global_load_dwordx4 v[116:119], v[112:113], off offset:512
	s_nop 0
	global_load_dwordx4 v[112:115], v[112:113], off offset:528

; __device__ __forceinline__ unsigned cvt_pk_bf16(float lo, float hi) { unsigned r; asm volatile("v_cvt_pk_bf16_f32 %0, %1, %2" : "=v"(r) : "v"(lo), "v"(hi)); return r; }
; __device__ __forceinline__ float bf2f(unsigned b) { return __uint_as_float(b << 16); }
;     __device__ __forceinline__ void operator()(const f32x4 (&acc)[2][2][4][2], const Unit& u, int wr, int wc, int fr, int fq) const {
;     ...
;                     const int col0 = u.pn * 256 + bj * 128 + wc * 32 + fq * 8;
;                     f32x4 x0 = (f32x4){0.f, 0.f, 0.f, 0.f}, x1 = x0;
;                     if (recon) {
;                         const v4u xb = __builtin_nontemporal_load((const v4u*)(XN + (size_t)row * D + col0));
;                         x0 = (f32x4){bf2f(xb.x & 0xffffu), bf2f(xb.x >> 16), bf2f(xb.y & 0xffffu), bf2f(xb.y >> 16)} * gi[bj][0] * ri;
;                         x1 = (f32x4){bf2f(xb.z & 0xffffu), bf2f(xb.z >> 16), bf2f(xb.w & 0xffffu), bf2f(xb.w >> 16)} * gi[bj][1] * ri;
;                     } else if (valid) { x0 = *(const f32x4*)(xr + col0); x1 = *(const f32x4*)(xr + col0 + 4); }
;                     const f32x4 v0 = acc[ai][bj][m][0] + x0, v1 = acc[ai][bj][m][1] + x1;
;                     ss += (v0[0] * v0[0] + v0[1] * v0[1]) + (v0[2] * v0[2] + v0[3] * v0[3]) + (v1[0] * v1[0] + v1[1] * v1[1]) + (v1[2] * v1[2] + v1[3] * v1[3]);
;                     if (valid && row >= MP) { *(f32x4*)(out + (size_t)row * D + col0) = v0; *(f32x4*)(out + (size_t)row * D + col0 + 4) = v1; }
;                     v4u w; w.x = cvt_pk_bf16(v0[0], v0[1]); w.y = cvt_pk_bf16(v0[2], v0[3]); w.z = cvt_pk_bf16(v1[0], v1[1]); w.w = cvt_pk_bf16(v1[2], v1[3]);
;                     *(v4u*)(XMIDB + (size_t)row * D + col0) = w;
;                 }
;                 ss += __shfl_xor(ss, 16); ss += __shfl_xor(ss, 32);
;                 if (fq == 0) atomicAdd(SS + row, ss);
.LBB0_731:
	s_waitcnt vmcnt(1)
	v_pk_add_f32 v[102:103], v[102:103], v[118:119]
	v_pk_add_f32 v[100:101], v[100:101], v[116:117]
	s_waitcnt vmcnt(0)
	v_pk_add_f32 v[98:99], v[98:99], v[114:115]
	s_andn2_b64 vcc, exec, s[14:15]
	v_pk_add_f32 v[96:97], v[96:97], v[112:113]
	s_cbranch_vccnz .LBB0_733
	v_lshl_add_u64 v[112:113], v[150:151], 2, v[126:127]
	global_store_dwordx4 v[112:113], v[100:103], off offset:512 sc1
	global_store_dwordx4 v[112:113], v[96:99], off offset:528 sc1
.LBB0_733:
	v_mul_f32_e32 v109, v109, v109
	v_fmac_f32_e32 v109, v108, v108
	v_mul_f32_e32 v108, v111, v111
	v_fmac_f32_e32 v108, v110, v110
	v_mul_f32_e32 v105, v105, v105
	v_add_f32_e32 v108, v109, v108
	v_fmac_f32_e32 v105, v104, v104
	v_add_f32_e32 v104, v108, v105
	v_mul_f32_e32 v105, v107, v107
	v_fmac_f32_e32 v105, v106, v106
	v_add_f32_e32 v104, v105, v104
	v_mul_f32_e32 v105, v101, v101
	v_mul_f32_e32 v106, v103, v103
	v_fmac_f32_e32 v105, v100, v100
	v_fmac_f32_e32 v106, v102, v102
	v_add_f32_e32 v105, v105, v106
	v_mul_f32_e32 v106, v97, v97
	v_fmac_f32_e32 v106, v96, v96
	v_add_f32_e32 v105, v105, v106
	v_mul_f32_e32 v106, v99, v99
	v_fmac_f32_e32 v106, v98, v98
	v_add_f32_e32 v105, v106, v105
	v_add_f32_e32 v106, v104, v105
	ds_bpermute_b32 v107, v128, v106
	v_cvt_pk_bf16_f32 v104, v100, v101
	v_cvt_pk_bf16_f32 v105, v102, v103
	s_waitcnt lgkmcnt(0)
	v_add_f32_e32 v100, v106, v107
	ds_bpermute_b32 v101, v129, v100
	v_cvt_pk_bf16_f32 v106, v96, v97
	v_lshl_add_u64 v[96:97], v[160:161], 1, v[122:123]
	v_cvt_pk_bf16_f32 v107, v98, v99
	global_store_dwordx4 v[96:97], v[104:107], off sc1
	s_and_saveexec_b64 s[14:15], s[10:11]
	s_cbranch_execz .LBB0_735
	v_lshl_add_u64 v[96:97], v[120:121], 2, s[40:41]
	s_waitcnt lgkmcnt(0)
	v_add_f32_e32 v98, v100, v101
	global_atomic_add_f32 v[96:97], v98, off

; __device__ __forceinline__ unsigned cvt_pk_bf16(float lo, float hi) { unsigned r; asm volatile("v_cvt_pk_bf16_f32 %0, %1, %2" : "=v"(r) : "v"(lo), "v"(hi)); return r; }
; __device__ __forceinline__ float bf2f(unsigned b) { return __uint_as_float(b << 16); }
;     __device__ __forceinline__ void operator()(const f32x4 (&acc)[2][2][4][2], const Unit& u, int wr, int wc, int fr, int fq) const {
;     ...
;                     const int col0 = u.pn * 256 + bj * 128 + wc * 32 + fq * 8;
;                     f32x4 x0 = (f32x4){0.f, 0.f, 0.f, 0.f}, x1 = x0;
;                     if (recon) {
;                         const v4u xb = __builtin_nontemporal_load((const v4u*)(XN + (size_t)row * D + col0));
;                         x0 = (f32x4){bf2f(xb.x & 0xffffu), bf2f(xb.x >> 16), bf2f(xb.y & 0xffffu), bf2f(xb.y >> 16)} * gi[bj][0] * ri;
;                         x1 = (f32x4){bf2f(xb.z & 0xffffu), bf2f(xb.z >> 16), bf2f(xb.w & 0xffffu), bf2f(xb.w >> 16)} * gi[bj][1] * ri;
;                     } else if (valid) { x0 = *(const f32x4*)(xr + col0); x1 = *(const f32x4*)(xr + col0 + 4); }
;                     const f32x4 v0 = acc[ai][bj][m][0] + x0, v1 = acc[ai][bj][m][1] + x1;
;                     ss += (v0[0] * v0[0] + v0[1] * v0[1]) + (v0[2] * v0[2] + v0[3] * v0[3]) + (v1[0] * v1[0] + v1[1] * v1[1]) + (v1[2] * v1[2] + v1[3] * v1[3]);
;                     if (valid && row >= MP) { *(f32x4*)(out + (size_t)row * D + col0) = v0; *(f32x4*)(out + (size_t)row * D + col0 + 4) = v1; }
;                     v4u w; w.x = cvt_pk_bf16(v0[0], v0[1]); w.y = cvt_pk_bf16(v0[2], v0[3]); w.z = cvt_pk_bf16(v1[0], v1[1]); w.w = cvt_pk_bf16(v1[2], v1[3]);
;                     *(v4u*)(XMIDB + (size_t)row * D + col0) = w;
.LBB0_739:
	v_lshlrev_b32_e32 v144, 10, v104
	s_waitcnt vmcnt(1)
	v_pk_add_f32 v[94:95], v[94:95], v[102:103]
	v_pk_add_f32 v[92:93], v[92:93], v[100:101]
	s_waitcnt vmcnt(0)
	v_pk_add_f32 v[90:91], v[90:91], v[98:99]
	v_pk_add_f32 v[88:89], v[88:89], v[96:97]
	s_andn2_b64 vcc, exec, s[56:57]
	v_lshl_add_u64 v[110:111], v[144:145], 2, s[16:17]
	s_cbranch_vccnz .LBB0_741
	v_lshl_add_u64 v[96:97], v[150:151], 2, v[110:111]
	global_store_dwordx4 v[96:97], v[92:95], off sc1
	global_store_dwordx4 v[96:97], v[88:91], off offset:16 sc1
.LBB0_741:
	v_lshlrev_b64 v[100:101], 11, v[104:105]
	v_lshl_add_u64 v[106:107], s[26:27], 0, v[100:101]
	v_cvt_pk_bf16_f32 v96, v92, v93
	v_cvt_pk_bf16_f32 v97, v94, v95
	v_cvt_pk_bf16_f32 v98, v88, v89
	v_cvt_pk_bf16_f32 v99, v90, v91
	v_lshl_add_u64 v[100:101], v[150:151], 1, v[106:107]
	global_store_dwordx4 v[100:101], v[96:99], off sc1
	v_mov_b32_e32 v100, 0
	v_mov_b32_e32 v101, 0
	v_mov_b32_e32 v102, 0
	v_mov_b32_e32 v103, 0
	v_mov_b32_e32 v96, 0
	v_mov_b32_e32 v97, 0
	v_mov_b32_e32 v98, 0
	v_mov_b32_e32 v99, 0
	s_and_saveexec_b64 s[56:57], s[14:15]
	s_cbranch_execz .LBB0_743
	v_lshl_add_u64 v[96:97], v[150:151], 2, v[108:109]
	global_load_dwordx4 v[100:103], v[96:97], off offset:512
	s_nop 0
	global_load_dwordx4 v[96:99], v[96:97], off offset:528

; __device__ __forceinline__ unsigned cvt_pk_bf16(float lo, float hi) { unsigned r; asm volatile("v_cvt_pk_bf16_f32 %0, %1, %2" : "=v"(r) : "v"(lo), "v"(hi)); return r; }
; __device__ __forceinline__ float bf2f(unsigned b) { return __uint_as_float(b << 16); }
;     __device__ __forceinline__ void operator()(const f32x4 (&acc)[2][2][4][2], const Unit& u, int wr, int wc, int fr, int fq) const {
;     ...
;                     const int col0 = u.pn * 256 + bj * 128 + wc * 32 + fq * 8;
;                     f32x4 x0 = (f32x4){0.f, 0.f, 0.f, 0.f}, x1 = x0;
;                     if (recon) {
;                         const v4u xb = __builtin_nontemporal_load((const v4u*)(XN + (size_t)row * D + col0));
;                         x0 = (f32x4){bf2f(xb.x & 0xffffu), bf2f(xb.x >> 16), bf2f(xb.y & 0xffffu), bf2f(xb.y >> 16)} * gi[bj][0] * ri;
;                         x1 = (f32x4){bf2f(xb.z & 0xffffu), bf2f(xb.z >> 16), bf2f(xb.w & 0xffffu), bf2f(xb.w >> 16)} * gi[bj][1] * ri;
;                     } else if (valid) { x0 = *(const f32x4*)(xr + col0); x1 = *(const f32x4*)(xr + col0 + 4); }
;                     const f32x4 v0 = acc[ai][bj][m][0] + x0, v1 = acc[ai][bj][m][1] + x1;
;                     ss += (v0[0] * v0[0] + v0[1] * v0[1]) + (v0[2] * v0[2] + v0[3] * v0[3]) + (v1[0] * v1[0] + v1[1] * v1[1]) + (v1[2] * v1[2] + v1[3] * v1[3]);
;                     if (valid && row >= MP) { *(f32x4*)(out + (size_t)row * D + col0) = v0; *(f32x4*)(out + (size_t)row * D + col0 + 4) = v1; }
;                     v4u w; w.x = cvt_pk_bf16(v0[0], v0[1]); w.y = cvt_pk_bf16(v0[2], v0[3]); w.z = cvt_pk_bf16(v1[0], v1[1]); w.w = cvt_pk_bf16(v1[2], v1[3]);
;                     *(v4u*)(XMIDB + (size_t)row * D + col0) = w;
;                 }
;                 ss += __shfl_xor(ss, 16); ss += __shfl_xor(ss, 32);
;                 if (fq == 0) atomicAdd(SS + row, ss);
.LBB0_745:
	s_waitcnt vmcnt(1)
	v_pk_add_f32 v[86:87], v[86:87], v[102:103]
	v_pk_add_f32 v[84:85], v[84:85], v[100:101]
	s_waitcnt vmcnt(0)
	v_pk_add_f32 v[82:83], v[82:83], v[98:99]
	s_andn2_b64 vcc, exec, s[14:15]
	v_pk_add_f32 v[80:81], v[80:81], v[96:97]
	s_cbranch_vccnz .LBB0_747
	v_lshl_add_u64 v[96:97], v[150:151], 2, v[110:111]
	global_store_dwordx4 v[96:97], v[84:87], off offset:512 sc1
	global_store_dwordx4 v[96:97], v[80:83], off offset:528 sc1
.LBB0_747:
	v_mul_f32_e32 v93, v93, v93
	v_fmac_f32_e32 v93, v92, v92
	v_mul_f32_e32 v92, v95, v95
	v_fmac_f32_e32 v92, v94, v94
	v_mul_f32_e32 v89, v89, v89
	v_add_f32_e32 v92, v93, v92
	v_fmac_f32_e32 v89, v88, v88
	v_add_f32_e32 v88, v92, v89
	v_mul_f32_e32 v89, v91, v91
	v_fmac_f32_e32 v89, v90, v90
	v_add_f32_e32 v88, v89, v88
	v_mul_f32_e32 v89, v85, v85
	v_mul_f32_e32 v90, v87, v87
	v_fmac_f32_e32 v89, v84, v84
	v_fmac_f32_e32 v90, v86, v86
	v_add_f32_e32 v89, v89, v90
	v_mul_f32_e32 v90, v81, v81
	v_fmac_f32_e32 v90, v80, v80
	v_add_f32_e32 v89, v89, v90
	v_mul_f32_e32 v90, v83, v83
	v_fmac_f32_e32 v90, v82, v82
	v_add_f32_e32 v89, v90, v89
	v_add_f32_e32 v90, v88, v89
	ds_bpermute_b32 v91, v128, v90
	v_cvt_pk_bf16_f32 v88, v84, v85
	v_cvt_pk_bf16_f32 v89, v86, v87
	s_waitcnt lgkmcnt(0)
	v_add_f32_e32 v84, v90, v91
	ds_bpermute_b32 v85, v129, v84
	v_cvt_pk_bf16_f32 v90, v80, v81
	v_lshl_add_u64 v[80:81], v[160:161], 1, v[106:107]
	v_cvt_pk_bf16_f32 v91, v82, v83
	global_store_dwordx4 v[80:81], v[88:91], off sc1
	s_and_saveexec_b64 s[14:15], s[10:11]
	s_cbranch_execz .LBB0_749
	v_lshl_add_u64 v[80:81], v[104:105], 2, s[40:41]
	s_waitcnt lgkmcnt(0)
	v_add_f32_e32 v82, v84, v85
	global_atomic_add_f32 v[80:81], v82, off

; __device__ __forceinline__ unsigned cvt_pk_bf16(float lo, float hi) { unsigned r; asm volatile("v_cvt_pk_bf16_f32 %0, %1, %2" : "=v"(r) : "v"(lo), "v"(hi)); return r; }
; __device__ __forceinline__ float bf2f(unsigned b) { return __uint_as_float(b << 16); }
;     __device__ __forceinline__ void operator()(const f32x4 (&acc)[2][2][4][2], const Unit& u, int wr, int wc, int fr, int fq) const {
;     ...
;                     const int col0 = u.pn * 256 + bj * 128 + wc * 32 + fq * 8;
;                     f32x4 x0 = (f32x4){0.f, 0.f, 0.f, 0.f}, x1 = x0;
;                     if (recon) {
;                         const v4u xb = __builtin_nontemporal_load((const v4u*)(XN + (size_t)row * D + col0));
;                         x0 = (f32x4){bf2f(xb.x & 0xffffu), bf2f(xb.x >> 16), bf2f(xb.y & 0xffffu), bf2f(xb.y >> 16)} * gi[bj][0] * ri;
;                         x1 = (f32x4){bf2f(xb.z & 0xffffu), bf2f(xb.z >> 16), bf2f(xb.w & 0xffffu), bf2f(xb.w >> 16)} * gi[bj][1] * ri;
;                     } else if (valid) { x0 = *(const f32x4*)(xr + col0); x1 = *(const f32x4*)(xr + col0 + 4); }
;                     const f32x4 v0 = acc[ai][bj][m][0] + x0, v1 = acc[ai][bj][m][1] + x1;
;                     ss += (v0[0] * v0[0] + v0[1] * v0[1]) + (v0[2] * v0[2] + v0[3] * v0[3]) + (v1[0] * v1[0] + v1[1] * v1[1]) + (v1[2] * v1[2] + v1[3] * v1[3]);
;                     if (valid && row >= MP) { *(f32x4*)(out + (size_t)row * D + col0) = v0; *(f32x4*)(out + (size_t)row * D + col0 + 4) = v1; }
;                     v4u w; w.x = cvt_pk_bf16(v0[0], v0[1]); w.y = cvt_pk_bf16(v0[2], v0[3]); w.z = cvt_pk_bf16(v1[0], v1[1]); w.w = cvt_pk_bf16(v1[2], v1[3]);
;                     *(v4u*)(XMIDB + (size_t)row * D + col0) = w;
.LBB0_753:
	v_lshlrev_b32_e32 v144, 10, v88
	s_waitcnt vmcnt(1)
	v_pk_add_f32 v[78:79], v[78:79], v[86:87]
	v_pk_add_f32 v[76:77], v[76:77], v[84:85]
	s_waitcnt vmcnt(0)
	v_pk_add_f32 v[74:75], v[74:75], v[82:83]
	v_pk_add_f32 v[72:73], v[72:73], v[80:81]
	s_andn2_b64 vcc, exec, s[56:57]
	v_lshl_add_u64 v[94:95], v[144:145], 2, s[16:17]
	s_cbranch_vccnz .LBB0_755
	v_lshl_add_u64 v[80:81], v[150:151], 2, v[94:95]
	global_store_dwordx4 v[80:81], v[76:79], off sc1
	global_store_dwordx4 v[80:81], v[72:75], off offset:16 sc1
.LBB0_755:
	v_lshlrev_b64 v[84:85], 11, v[88:89]
	v_lshl_add_u64 v[90:91], s[26:27], 0, v[84:85]
	v_cvt_pk_bf16_f32 v80, v76, v77
	v_cvt_pk_bf16_f32 v81, v78, v79
	v_cvt_pk_bf16_f32 v82, v72, v73
	v_cvt_pk_bf16_f32 v83, v74, v75
	v_lshl_add_u64 v[84:85], v[150:151], 1, v[90:91]
	global_store_dwordx4 v[84:85], v[80:83], off sc1
	v_mov_b32_e32 v84, 0
	v_mov_b32_e32 v85, 0
	v_mov_b32_e32 v86, 0
	v_mov_b32_e32 v87, 0
	v_mov_b32_e32 v80, 0
	v_mov_b32_e32 v81, 0
	v_mov_b32_e32 v82, 0
	v_mov_b32_e32 v83, 0
	s_and_saveexec_b64 s[56:57], s[14:15]
	s_cbranch_execz .LBB0_757
	v_lshl_add_u64 v[80:81], v[150:151], 2, v[92:93]
	global_load_dwordx4 v[84:87], v[80:81], off offset:512
	s_nop 0
	global_load_dwordx4 v[80:83], v[80:81], off offset:528

; __device__ __forceinline__ unsigned cvt_pk_bf16(float lo, float hi) { unsigned r; asm volatile("v_cvt_pk_bf16_f32 %0, %1, %2" : "=v"(r) : "v"(lo), "v"(hi)); return r; }
; __device__ __forceinline__ float bf2f(unsigned b) { return __uint_as_float(b << 16); }
;     __device__ __forceinline__ void operator()(const f32x4 (&acc)[2][2][4][2], const Unit& u, int wr, int wc, int fr, int fq) const {
;     ...
;                     const int col0 = u.pn * 256 + bj * 128 + wc * 32 + fq * 8;
;                     f32x4 x0 = (f32x4){0.f, 0.f, 0.f, 0.f}, x1 = x0;
;                     if (recon) {
;                         const v4u xb = __builtin_nontemporal_load((const v4u*)(XN + (size_t)row * D + col0));
;                         x0 = (f32x4){bf2f(xb.x & 0xffffu), bf2f(xb.x >> 16), bf2f(xb.y & 0xffffu), bf2f(xb.y >> 16)} * gi[bj][0] * ri;
;                         x1 = (f32x4){bf2f(xb.z & 0xffffu), bf2f(xb.z >> 16), bf2f(xb.w & 0xffffu), bf2f(xb.w >> 16)} * gi[bj][1] * ri;
;                     } else if (valid) { x0 = *(const f32x4*)(xr + col0); x1 = *(const f32x4*)(xr + col0 + 4); }
;                     const f32x4 v0 = acc[ai][bj][m][0] + x0, v1 = acc[ai][bj][m][1] + x1;
;                     ss += (v0[0] * v0[0] + v0[1] * v0[1]) + (v0[2] * v0[2] + v0[3] * v0[3]) + (v1[0] * v1[0] + v1[1] * v1[1]) + (v1[2] * v1[2] + v1[3] * v1[3]);
;                     if (valid && row >= MP) { *(f32x4*)(out + (size_t)row * D + col0) = v0; *(f32x4*)(out + (size_t)row * D + col0 + 4) = v1; }
;                     v4u w; w.x = cvt_pk_bf16(v0[0], v0[1]); w.y = cvt_pk_bf16(v0[2], v0[3]); w.z = cvt_pk_bf16(v1[0], v1[1]); w.w = cvt_pk_bf16(v1[2], v1[3]);
;                     *(v4u*)(XMIDB + (size_t)row * D + col0) = w;
;                 }
;                 ss += __shfl_xor(ss, 16); ss += __shfl_xor(ss, 32);
;                 if (fq == 0) atomicAdd(SS + row, ss);
.LBB0_759:
	s_waitcnt vmcnt(1)
	v_pk_add_f32 v[70:71], v[70:71], v[86:87]
	v_pk_add_f32 v[68:69], v[68:69], v[84:85]
	s_waitcnt vmcnt(0)
	v_pk_add_f32 v[66:67], v[66:67], v[82:83]
	s_andn2_b64 vcc, exec, s[12:13]
	v_pk_add_f32 v[64:65], v[64:65], v[80:81]
	s_cbranch_vccnz .LBB0_761
	v_lshl_add_u64 v[80:81], v[150:151], 2, v[94:95]
	global_store_dwordx4 v[80:81], v[68:71], off offset:512 sc1
	global_store_dwordx4 v[80:81], v[64:67], off offset:528 sc1
.LBB0_761:
	v_mul_f32_e32 v77, v77, v77
	v_fmac_f32_e32 v77, v76, v76
	v_mul_f32_e32 v76, v79, v79
	v_fmac_f32_e32 v76, v78, v78
	v_mul_f32_e32 v73, v73, v73
	v_add_f32_e32 v76, v77, v76
	v_fmac_f32_e32 v73, v72, v72
	v_add_f32_e32 v72, v76, v73
	v_mul_f32_e32 v73, v75, v75
	v_fmac_f32_e32 v73, v74, v74
	v_add_f32_e32 v72, v73, v72
	v_mul_f32_e32 v73, v69, v69
	v_mul_f32_e32 v74, v71, v71
	v_fmac_f32_e32 v73, v68, v68
	v_fmac_f32_e32 v74, v70, v70
	v_add_f32_e32 v73, v73, v74
	v_mul_f32_e32 v74, v65, v65
	v_fmac_f32_e32 v74, v64, v64
	v_add_f32_e32 v73, v73, v74
	v_mul_f32_e32 v74, v67, v67
	v_fmac_f32_e32 v74, v66, v66
	v_add_f32_e32 v73, v74, v73
	v_add_f32_e32 v74, v72, v73
	ds_bpermute_b32 v75, v128, v74
	v_cvt_pk_bf16_f32 v72, v68, v69
	v_cvt_pk_bf16_f32 v73, v70, v71
	s_waitcnt lgkmcnt(0)
	v_add_f32_e32 v68, v74, v75
	ds_bpermute_b32 v69, v129, v68
	v_cvt_pk_bf16_f32 v74, v64, v65
	v_lshl_add_u64 v[64:65], v[160:161], 1, v[90:91]
	v_cvt_pk_bf16_f32 v75, v66, v67
	global_store_dwordx4 v[64:65], v[72:75], off sc1
	s_and_saveexec_b64 s[12:13], s[10:11]
	s_cbranch_execz .LBB0_763
	v_lshl_add_u64 v[64:65], v[88:89], 2, s[40:41]
	s_waitcnt lgkmcnt(0)
	v_add_f32_e32 v66, v68, v69
	global_atomic_add_f32 v[64:65], v66, off

; __device__ __forceinline__ unsigned cvt_pk_bf16(float lo, float hi) { unsigned r; asm volatile("v_cvt_pk_bf16_f32 %0, %1, %2" : "=v"(r) : "v"(lo), "v"(hi)); return r; }
; __device__ __forceinline__ float bf2f(unsigned b) { return __uint_as_float(b << 16); }
;     __device__ __forceinline__ void operator()(const f32x4 (&acc)[2][2][4][2], const Unit& u, int wr, int wc, int fr, int fq) const {
;     ...
;                     const int col0 = u.pn * 256 + bj * 128 + wc * 32 + fq * 8;
;                     f32x4 x0 = (f32x4){0.f, 0.f, 0.f, 0.f}, x1 = x0;
;                     if (recon) {
;                         const v4u xb = __builtin_nontemporal_load((const v4u*)(XN + (size_t)row * D + col0));
;                         x0 = (f32x4){bf2f(xb.x & 0xffffu), bf2f(xb.x >> 16), bf2f(xb.y & 0xffffu), bf2f(xb.y >> 16)} * gi[bj][0] * ri;
;                         x1 = (f32x4){bf2f(xb.z & 0xffffu), bf2f(xb.z >> 16), bf2f(xb.w & 0xffffu), bf2f(xb.w >> 16)} * gi[bj][1] * ri;
;                     } else if (valid) { x0 = *(const f32x4*)(xr + col0); x1 = *(const f32x4*)(xr + col0 + 4); }
;                     const f32x4 v0 = acc[ai][bj][m][0] + x0, v1 = acc[ai][bj][m][1] + x1;
;                     ss += (v0[0] * v0[0] + v0[1] * v0[1]) + (v0[2] * v0[2] + v0[3] * v0[3]) + (v1[0] * v1[0] + v1[1] * v1[1]) + (v1[2] * v1[2] + v1[3] * v1[3]);
;                     if (valid && row >= MP) { *(f32x4*)(out + (size_t)row * D + col0) = v0; *(f32x4*)(out + (size_t)row * D + col0 + 4) = v1; }
;                     v4u w; w.x = cvt_pk_bf16(v0[0], v0[1]); w.y = cvt_pk_bf16(v0[2], v0[3]); w.z = cvt_pk_bf16(v1[0], v1[1]); w.w = cvt_pk_bf16(v1[2], v1[3]);
;                     *(v4u*)(XMIDB + (size_t)row * D + col0) = w;
.LBB0_767:
	v_lshlrev_b32_e32 v144, 10, v72
	s_waitcnt vmcnt(1)
	v_pk_add_f32 v[62:63], v[62:63], v[70:71]
	v_pk_add_f32 v[60:61], v[60:61], v[68:69]
	s_waitcnt vmcnt(0)
	v_pk_add_f32 v[58:59], v[58:59], v[66:67]
	v_pk_add_f32 v[56:57], v[56:57], v[64:65]
	s_andn2_b64 vcc, exec, s[56:57]
	v_lshl_add_u64 v[78:79], v[144:145], 2, s[16:17]
	s_cbranch_vccnz .LBB0_769
	v_lshl_add_u64 v[64:65], v[150:151], 2, v[78:79]
	global_store_dwordx4 v[64:65], v[60:63], off sc1
	global_store_dwordx4 v[64:65], v[56:59], off offset:16 sc1
.LBB0_769:
	v_lshlrev_b64 v[68:69], 11, v[72:73]
	v_lshl_add_u64 v[74:75], s[26:27], 0, v[68:69]
	v_cvt_pk_bf16_f32 v64, v60, v61
	v_cvt_pk_bf16_f32 v65, v62, v63
	v_cvt_pk_bf16_f32 v66, v56, v57
	v_cvt_pk_bf16_f32 v67, v58, v59
	v_lshl_add_u64 v[68:69], v[150:151], 1, v[74:75]
	global_store_dwordx4 v[68:69], v[64:67], off sc1
	v_mov_b32_e32 v68, 0
	v_mov_b32_e32 v69, 0
	v_mov_b32_e32 v70, 0
	v_mov_b32_e32 v71, 0
	v_mov_b32_e32 v64, 0
	v_mov_b32_e32 v65, 0
	v_mov_b32_e32 v66, 0
	v_mov_b32_e32 v67, 0
	s_and_saveexec_b64 s[56:57], s[12:13]
	s_cbranch_execz .LBB0_771
	v_lshl_add_u64 v[64:65], v[150:151], 2, v[76:77]
	global_load_dwordx4 v[68:71], v[64:65], off offset:512
	s_nop 0
	global_load_dwordx4 v[64:67], v[64:65], off offset:528

; __device__ __forceinline__ unsigned cvt_pk_bf16(float lo, float hi) { unsigned r; asm volatile("v_cvt_pk_bf16_f32 %0, %1, %2" : "=v"(r) : "v"(lo), "v"(hi)); return r; }
; __device__ __forceinline__ float bf2f(unsigned b) { return __uint_as_float(b << 16); }
;     __device__ __forceinline__ void operator()(const f32x4 (&acc)[2][2][4][2], const Unit& u, int wr, int wc, int fr, int fq) const {
;     ...
;                     const int col0 = u.pn * 256 + bj * 128 + wc * 32 + fq * 8;
;                     f32x4 x0 = (f32x4){0.f, 0.f, 0.f, 0.f}, x1 = x0;
;                     if (recon) {
;                         const v4u xb = __builtin_nontemporal_load((const v4u*)(XN + (size_t)row * D + col0));
;                         x0 = (f32x4){bf2f(xb.x & 0xffffu), bf2f(xb.x >> 16), bf2f(xb.y & 0xffffu), bf2f(xb.y >> 16)} * gi[bj][0] * ri;
;                         x1 = (f32x4){bf2f(xb.z & 0xffffu), bf2f(xb.z >> 16), bf2f(xb.w & 0xffffu), bf2f(xb.w >> 16)} * gi[bj][1] * ri;
;                     } else if (valid) { x0 = *(const f32x4*)(xr + col0); x1 = *(const f32x4*)(xr + col0 + 4); }
;                     const f32x4 v0 = acc[ai][bj][m][0] + x0, v1 = acc[ai][bj][m][1] + x1;
;                     ss += (v0[0] * v0[0] + v0[1] * v0[1]) + (v0[2] * v0[2] + v0[3] * v0[3]) + (v1[0] * v1[0] + v1[1] * v1[1]) + (v1[2] * v1[2] + v1[3] * v1[3]);
;                     if (valid && row >= MP) { *(f32x4*)(out + (size_t)row * D + col0) = v0; *(f32x4*)(out + (size_t)row * D + col0 + 4) = v1; }
;                     v4u w; w.x = cvt_pk_bf16(v0[0], v0[1]); w.y = cvt_pk_bf16(v0[2], v0[3]); w.z = cvt_pk_bf16(v1[0], v1[1]); w.w = cvt_pk_bf16(v1[2], v1[3]);
;                     *(v4u*)(XMIDB + (size_t)row * D + col0) = w;
;                 }
;                 ss += __shfl_xor(ss, 16); ss += __shfl_xor(ss, 32);
;                 if (fq == 0) atomicAdd(SS + row, ss);
.LBB0_773:
	s_waitcnt vmcnt(1)
	v_pk_add_f32 v[54:55], v[54:55], v[70:71]
	v_pk_add_f32 v[52:53], v[52:53], v[68:69]
	s_waitcnt vmcnt(0)
	v_pk_add_f32 v[50:51], v[50:51], v[66:67]
	s_andn2_b64 vcc, exec, s[14:15]
	v_pk_add_f32 v[48:49], v[48:49], v[64:65]
	s_cbranch_vccnz .LBB0_775
	v_lshl_add_u64 v[64:65], v[150:151], 2, v[78:79]
	global_store_dwordx4 v[64:65], v[52:55], off offset:512 sc1
	global_store_dwordx4 v[64:65], v[48:51], off offset:528 sc1
.LBB0_775:
	v_mul_f32_e32 v61, v61, v61
	v_fmac_f32_e32 v61, v60, v60
	v_mul_f32_e32 v60, v63, v63
	v_fmac_f32_e32 v60, v62, v62
	v_mul_f32_e32 v57, v57, v57
	v_add_f32_e32 v60, v61, v60
	v_fmac_f32_e32 v57, v56, v56
	v_add_f32_e32 v56, v60, v57
	v_mul_f32_e32 v57, v59, v59
	v_fmac_f32_e32 v57, v58, v58
	v_add_f32_e32 v56, v57, v56
	v_mul_f32_e32 v57, v53, v53
	v_mul_f32_e32 v58, v55, v55
	v_fmac_f32_e32 v57, v52, v52
	v_fmac_f32_e32 v58, v54, v54
	v_add_f32_e32 v57, v57, v58
	v_mul_f32_e32 v58, v49, v49
	v_fmac_f32_e32 v58, v48, v48
	v_add_f32_e32 v57, v57, v58
	v_mul_f32_e32 v58, v51, v51
	v_fmac_f32_e32 v58, v50, v50
	v_add_f32_e32 v57, v58, v57
	v_add_f32_e32 v58, v56, v57
	ds_bpermute_b32 v59, v128, v58
	v_cvt_pk_bf16_f32 v56, v52, v53
	v_cvt_pk_bf16_f32 v57, v54, v55
	s_waitcnt lgkmcnt(0)
	v_add_f32_e32 v52, v58, v59
	ds_bpermute_b32 v53, v129, v52
	v_cvt_pk_bf16_f32 v58, v48, v49
	v_lshl_add_u64 v[48:49], v[160:161], 1, v[74:75]
	v_cvt_pk_bf16_f32 v59, v50, v51
	global_store_dwordx4 v[48:49], v[56:59], off sc1
	s_and_saveexec_b64 s[14:15], s[10:11]
	s_cbranch_execz .LBB0_777
	v_lshl_add_u64 v[48:49], v[72:73], 2, s[40:41]
	s_waitcnt lgkmcnt(0)
	v_add_f32_e32 v50, v52, v53
	global_atomic_add_f32 v[48:49], v50, off

; __device__ __forceinline__ unsigned cvt_pk_bf16(float lo, float hi) { unsigned r; asm volatile("v_cvt_pk_bf16_f32 %0, %1, %2" : "=v"(r) : "v"(lo), "v"(hi)); return r; }
; __device__ __forceinline__ float bf2f(unsigned b) { return __uint_as_float(b << 16); }
;     __device__ __forceinline__ void operator()(const f32x4 (&acc)[2][2][4][2], const Unit& u, int wr, int wc, int fr, int fq) const {
;     ...
;                     const int col0 = u.pn * 256 + bj * 128 + wc * 32 + fq * 8;
;                     f32x4 x0 = (f32x4){0.f, 0.f, 0.f, 0.f}, x1 = x0;
;                     if (recon) {
;                         const v4u xb = __builtin_nontemporal_load((const v4u*)(XN + (size_t)row * D + col0));
;                         x0 = (f32x4){bf2f(xb.x & 0xffffu), bf2f(xb.x >> 16), bf2f(xb.y & 0xffffu), bf2f(xb.y >> 16)} * gi[bj][0] * ri;
;                         x1 = (f32x4){bf2f(xb.z & 0xffffu), bf2f(xb.z >> 16), bf2f(xb.w & 0xffffu), bf2f(xb.w >> 16)} * gi[bj][1] * ri;
;                     } else if (valid) { x0 = *(const f32x4*)(xr + col0); x1 = *(const f32x4*)(xr + col0 + 4); }
;                     const f32x4 v0 = acc[ai][bj][m][0] + x0, v1 = acc[ai][bj][m][1] + x1;
;                     ss += (v0[0] * v0[0] + v0[1] * v0[1]) + (v0[2] * v0[2] + v0[3] * v0[3]) + (v1[0] * v1[0] + v1[1] * v1[1]) + (v1[2] * v1[2] + v1[3] * v1[3]);
;                     if (valid && row >= MP) { *(f32x4*)(out + (size_t)row * D + col0) = v0; *(f32x4*)(out + (size_t)row * D + col0 + 4) = v1; }
;                     v4u w; w.x = cvt_pk_bf16(v0[0], v0[1]); w.y = cvt_pk_bf16(v0[2], v0[3]); w.z = cvt_pk_bf16(v1[0], v1[1]); w.w = cvt_pk_bf16(v1[2], v1[3]);
;                     *(v4u*)(XMIDB + (size_t)row * D + col0) = w;
.LBB0_781:
	v_lshlrev_b32_e32 v144, 10, v56
	s_waitcnt vmcnt(1)
	v_pk_add_f32 v[46:47], v[46:47], v[54:55]
	v_pk_add_f32 v[44:45], v[44:45], v[52:53]
	s_waitcnt vmcnt(0)
	v_pk_add_f32 v[42:43], v[42:43], v[50:51]
	v_pk_add_f32 v[40:41], v[40:41], v[48:49]
	s_andn2_b64 vcc, exec, s[56:57]
	v_lshl_add_u64 v[62:63], v[144:145], 2, s[16:17]
	s_cbranch_vccnz .LBB0_783
	v_lshl_add_u64 v[48:49], v[150:151], 2, v[62:63]
	global_store_dwordx4 v[48:49], v[44:47], off sc1
	global_store_dwordx4 v[48:49], v[40:43], off offset:16 sc1
.LBB0_783:
	v_lshlrev_b64 v[52:53], 11, v[56:57]
	v_lshl_add_u64 v[58:59], s[26:27], 0, v[52:53]
	v_cvt_pk_bf16_f32 v48, v44, v45
	v_cvt_pk_bf16_f32 v49, v46, v47
	v_cvt_pk_bf16_f32 v50, v40, v41
	v_cvt_pk_bf16_f32 v51, v42, v43
	v_lshl_add_u64 v[52:53], v[150:151], 1, v[58:59]
	global_store_dwordx4 v[52:53], v[48:51], off sc1
	v_mov_b32_e32 v52, 0
	v_mov_b32_e32 v53, 0
	v_mov_b32_e32 v54, 0
	v_mov_b32_e32 v55, 0
	v_mov_b32_e32 v48, 0
	v_mov_b32_e32 v49, 0
	v_mov_b32_e32 v50, 0
	v_mov_b32_e32 v51, 0
	s_and_saveexec_b64 s[56:57], s[14:15]
	s_cbranch_execz .LBB0_785
	v_lshl_add_u64 v[48:49], v[150:151], 2, v[60:61]
	global_load_dwordx4 v[52:55], v[48:49], off offset:512
	s_nop 0
	global_load_dwordx4 v[48:51], v[48:49], off offset:528

; __device__ __forceinline__ unsigned cvt_pk_bf16(float lo, float hi) { unsigned r; asm volatile("v_cvt_pk_bf16_f32 %0, %1, %2" : "=v"(r) : "v"(lo), "v"(hi)); return r; }
; __device__ __forceinline__ float bf2f(unsigned b) { return __uint_as_float(b << 16); }
;     __device__ __forceinline__ void operator()(const f32x4 (&acc)[2][2][4][2], const Unit& u, int wr, int wc, int fr, int fq) const {
;     ...
;                     const int col0 = u.pn * 256 + bj * 128 + wc * 32 + fq * 8;
;                     f32x4 x0 = (f32x4){0.f, 0.f, 0.f, 0.f}, x1 = x0;
;                     if (recon) {
;                         const v4u xb = __builtin_nontemporal_load((const v4u*)(XN + (size_t)row * D + col0));
;                         x0 = (f32x4){bf2f(xb.x & 0xffffu), bf2f(xb.x >> 16), bf2f(xb.y & 0xffffu), bf2f(xb.y >> 16)} * gi[bj][0] * ri;
;                         x1 = (f32x4){bf2f(xb.z & 0xffffu), bf2f(xb.z >> 16), bf2f(xb.w & 0xffffu), bf2f(xb.w >> 16)} * gi[bj][1] * ri;
;                     } else if (valid) { x0 = *(const f32x4*)(xr + col0); x1 = *(const f32x4*)(xr + col0 + 4); }
;                     const f32x4 v0 = acc[ai][bj][m][0] + x0, v1 = acc[ai][bj][m][1] + x1;
;                     ss += (v0[0] * v0[0] + v0[1] * v0[1]) + (v0[2] * v0[2] + v0[3] * v0[3]) + (v1[0] * v1[0] + v1[1] * v1[1]) + (v1[2] * v1[2] + v1[3] * v1[3]);
;                     if (valid && row >= MP) { *(f32x4*)(out + (size_t)row * D + col0) = v0; *(f32x4*)(out + (size_t)row * D + col0 + 4) = v1; }
;                     v4u w; w.x = cvt_pk_bf16(v0[0], v0[1]); w.y = cvt_pk_bf16(v0[2], v0[3]); w.z = cvt_pk_bf16(v1[0], v1[1]); w.w = cvt_pk_bf16(v1[2], v1[3]);
;                     *(v4u*)(XMIDB + (size_t)row * D + col0) = w;
;                 }
;                 ss += __shfl_xor(ss, 16); ss += __shfl_xor(ss, 32);
;                 if (fq == 0) atomicAdd(SS + row, ss);
.LBB0_787:
	s_waitcnt vmcnt(1)
	v_pk_add_f32 v[38:39], v[38:39], v[54:55]
	v_pk_add_f32 v[36:37], v[36:37], v[52:53]
	s_waitcnt vmcnt(0)
	v_pk_add_f32 v[34:35], v[34:35], v[50:51]
	s_andn2_b64 vcc, exec, s[14:15]
	v_pk_add_f32 v[32:33], v[32:33], v[48:49]
	s_cbranch_vccnz .LBB0_789
	v_lshl_add_u64 v[48:49], v[150:151], 2, v[62:63]
	global_store_dwordx4 v[48:49], v[36:39], off offset:512 sc1
	global_store_dwordx4 v[48:49], v[32:35], off offset:528 sc1
.LBB0_789:
	v_mul_f32_e32 v45, v45, v45
	v_fmac_f32_e32 v45, v44, v44
	v_mul_f32_e32 v44, v47, v47
	v_fmac_f32_e32 v44, v46, v46
	v_mul_f32_e32 v41, v41, v41
	v_add_f32_e32 v44, v45, v44
	v_fmac_f32_e32 v41, v40, v40
	v_add_f32_e32 v40, v44, v41
	v_mul_f32_e32 v41, v43, v43
	v_fmac_f32_e32 v41, v42, v42
	v_add_f32_e32 v40, v41, v40
	v_mul_f32_e32 v41, v37, v37
	v_mul_f32_e32 v42, v39, v39
	v_fmac_f32_e32 v41, v36, v36
	v_fmac_f32_e32 v42, v38, v38
	v_add_f32_e32 v41, v41, v42
	v_mul_f32_e32 v42, v33, v33
	v_fmac_f32_e32 v42, v32, v32
	v_add_f32_e32 v41, v41, v42
	v_mul_f32_e32 v42, v35, v35
	v_fmac_f32_e32 v42, v34, v34
	v_add_f32_e32 v41, v42, v41
	v_add_f32_e32 v42, v40, v41
	ds_bpermute_b32 v43, v128, v42
	v_cvt_pk_bf16_f32 v40, v36, v37
	v_cvt_pk_bf16_f32 v41, v38, v39
	s_waitcnt lgkmcnt(0)
	v_add_f32_e32 v36, v42, v43
	ds_bpermute_b32 v37, v129, v36
	v_cvt_pk_bf16_f32 v42, v32, v33
	v_lshl_add_u64 v[32:33], v[160:161], 1, v[58:59]
	v_cvt_pk_bf16_f32 v43, v34, v35
	global_store_dwordx4 v[32:33], v[40:43], off sc1
	s_and_saveexec_b64 s[14:15], s[10:11]
	s_cbranch_execz .LBB0_791
	v_lshl_add_u64 v[32:33], v[56:57], 2, s[40:41]
	s_waitcnt lgkmcnt(0)
	v_add_f32_e32 v34, v36, v37
	global_atomic_add_f32 v[32:33], v34, off

; __device__ __forceinline__ unsigned cvt_pk_bf16(float lo, float hi) { unsigned r; asm volatile("v_cvt_pk_bf16_f32 %0, %1, %2" : "=v"(r) : "v"(lo), "v"(hi)); return r; }
; __device__ __forceinline__ float bf2f(unsigned b) { return __uint_as_float(b << 16); }
;     __device__ __forceinline__ void operator()(const f32x4 (&acc)[2][2][4][2], const Unit& u, int wr, int wc, int fr, int fq) const {
;     ...
;                     const int col0 = u.pn * 256 + bj * 128 + wc * 32 + fq * 8;
;                     f32x4 x0 = (f32x4){0.f, 0.f, 0.f, 0.f}, x1 = x0;
;                     if (recon) {
;                         const v4u xb = __builtin_nontemporal_load((const v4u*)(XN + (size_t)row * D + col0));
;                         x0 = (f32x4){bf2f(xb.x & 0xffffu), bf2f(xb.x >> 16), bf2f(xb.y & 0xffffu), bf2f(xb.y >> 16)} * gi[bj][0] * ri;
;                         x1 = (f32x4){bf2f(xb.z & 0xffffu), bf2f(xb.z >> 16), bf2f(xb.w & 0xffffu), bf2f(xb.w >> 16)} * gi[bj][1] * ri;
;                     } else if (valid) { x0 = *(const f32x4*)(xr + col0); x1 = *(const f32x4*)(xr + col0 + 4); }
;                     const f32x4 v0 = acc[ai][bj][m][0] + x0, v1 = acc[ai][bj][m][1] + x1;
;                     ss += (v0[0] * v0[0] + v0[1] * v0[1]) + (v0[2] * v0[2] + v0[3] * v0[3]) + (v1[0] * v1[0] + v1[1] * v1[1]) + (v1[2] * v1[2] + v1[3] * v1[3]);
;                     if (valid && row >= MP) { *(f32x4*)(out + (size_t)row * D + col0) = v0; *(f32x4*)(out + (size_t)row * D + col0 + 4) = v1; }
;                     v4u w; w.x = cvt_pk_bf16(v0[0], v0[1]); w.y = cvt_pk_bf16(v0[2], v0[3]); w.z = cvt_pk_bf16(v1[0], v1[1]); w.w = cvt_pk_bf16(v1[2], v1[3]);
;                     *(v4u*)(XMIDB + (size_t)row * D + col0) = w;
.LBB0_795:
	v_lshlrev_b32_e32 v144, 10, v40
	s_waitcnt vmcnt(1)
	v_pk_add_f32 v[30:31], v[30:31], v[38:39]
	v_pk_add_f32 v[28:29], v[28:29], v[36:37]
	s_waitcnt vmcnt(0)
	v_pk_add_f32 v[26:27], v[26:27], v[34:35]
	v_pk_add_f32 v[24:25], v[24:25], v[32:33]
	s_andn2_b64 vcc, exec, s[56:57]
	v_lshl_add_u64 v[46:47], v[144:145], 2, s[16:17]
	s_cbranch_vccnz .LBB0_797
	v_lshl_add_u64 v[32:33], v[150:151], 2, v[46:47]
	global_store_dwordx4 v[32:33], v[28:31], off sc1
	global_store_dwordx4 v[32:33], v[24:27], off offset:16 sc1
.LBB0_797:
	v_lshlrev_b64 v[36:37], 11, v[40:41]
	v_lshl_add_u64 v[42:43], s[26:27], 0, v[36:37]
	v_cvt_pk_bf16_f32 v32, v28, v29
	v_cvt_pk_bf16_f32 v33, v30, v31
	v_cvt_pk_bf16_f32 v34, v24, v25
	v_cvt_pk_bf16_f32 v35, v26, v27
	v_lshl_add_u64 v[36:37], v[150:151], 1, v[42:43]
	global_store_dwordx4 v[36:37], v[32:35], off sc1
	v_mov_b32_e32 v36, 0
	v_mov_b32_e32 v37, 0
	v_mov_b32_e32 v38, 0
	v_mov_b32_e32 v39, 0
	v_mov_b32_e32 v32, 0
	v_mov_b32_e32 v33, 0
	v_mov_b32_e32 v34, 0
	v_mov_b32_e32 v35, 0
	s_and_saveexec_b64 s[56:57], s[14:15]
	s_cbranch_execz .LBB0_799
	v_lshl_add_u64 v[32:33], v[150:151], 2, v[44:45]
	global_load_dwordx4 v[36:39], v[32:33], off offset:512
	s_nop 0
	global_load_dwordx4 v[32:35], v[32:33], off offset:528

; __device__ __forceinline__ unsigned cvt_pk_bf16(float lo, float hi) { unsigned r; asm volatile("v_cvt_pk_bf16_f32 %0, %1, %2" : "=v"(r) : "v"(lo), "v"(hi)); return r; }
; __device__ __forceinline__ float bf2f(unsigned b) { return __uint_as_float(b << 16); }
;     __device__ __forceinline__ void operator()(const f32x4 (&acc)[2][2][4][2], const Unit& u, int wr, int wc, int fr, int fq) const {
;     ...
;                     const int col0 = u.pn * 256 + bj * 128 + wc * 32 + fq * 8;
;                     f32x4 x0 = (f32x4){0.f, 0.f, 0.f, 0.f}, x1 = x0;
;                     if (recon) {
;                         const v4u xb = __builtin_nontemporal_load((const v4u*)(XN + (size_t)row * D + col0));
;                         x0 = (f32x4){bf2f(xb.x & 0xffffu), bf2f(xb.x >> 16), bf2f(xb.y & 0xffffu), bf2f(xb.y >> 16)} * gi[bj][0] * ri;
;                         x1 = (f32x4){bf2f(xb.z & 0xffffu), bf2f(xb.z >> 16), bf2f(xb.w & 0xffffu), bf2f(xb.w >> 16)} * gi[bj][1] * ri;
;                     } else if (valid) { x0 = *(const f32x4*)(xr + col0); x1 = *(const f32x4*)(xr + col0 + 4); }
;                     const f32x4 v0 = acc[ai][bj][m][0] + x0, v1 = acc[ai][bj][m][1] + x1;
;                     ss += (v0[0] * v0[0] + v0[1] * v0[1]) + (v0[2] * v0[2] + v0[3] * v0[3]) + (v1[0] * v1[0] + v1[1] * v1[1]) + (v1[2] * v1[2] + v1[3] * v1[3]);
;                     if (valid && row >= MP) { *(f32x4*)(out + (size_t)row * D + col0) = v0; *(f32x4*)(out + (size_t)row * D + col0 + 4) = v1; }
;                     v4u w; w.x = cvt_pk_bf16(v0[0], v0[1]); w.y = cvt_pk_bf16(v0[2], v0[3]); w.z = cvt_pk_bf16(v1[0], v1[1]); w.w = cvt_pk_bf16(v1[2], v1[3]);
;                     *(v4u*)(XMIDB + (size_t)row * D + col0) = w;
;                 }
;                 ss += __shfl_xor(ss, 16); ss += __shfl_xor(ss, 32);
;                 if (fq == 0) atomicAdd(SS + row, ss);
.LBB0_801:
	s_waitcnt vmcnt(1)
	v_pk_add_f32 v[22:23], v[22:23], v[38:39]
	v_pk_add_f32 v[20:21], v[20:21], v[36:37]
	s_waitcnt vmcnt(0)
	v_pk_add_f32 v[18:19], v[18:19], v[34:35]
	s_andn2_b64 vcc, exec, s[14:15]
	v_pk_add_f32 v[16:17], v[16:17], v[32:33]
	s_cbranch_vccnz .LBB0_803
	v_lshl_add_u64 v[32:33], v[150:151], 2, v[46:47]
	global_store_dwordx4 v[32:33], v[20:23], off offset:512 sc1
	global_store_dwordx4 v[32:33], v[16:19], off offset:528 sc1
.LBB0_803:
	v_mul_f32_e32 v29, v29, v29
	v_fmac_f32_e32 v29, v28, v28
	v_mul_f32_e32 v28, v31, v31
	v_fmac_f32_e32 v28, v30, v30
	v_mul_f32_e32 v25, v25, v25
	v_add_f32_e32 v28, v29, v28
	v_fmac_f32_e32 v25, v24, v24
	v_add_f32_e32 v24, v28, v25
	v_mul_f32_e32 v25, v27, v27
	v_fmac_f32_e32 v25, v26, v26
	v_add_f32_e32 v24, v25, v24
	v_mul_f32_e32 v25, v21, v21
	v_mul_f32_e32 v26, v23, v23
	v_fmac_f32_e32 v25, v20, v20
	v_fmac_f32_e32 v26, v22, v22
	v_add_f32_e32 v25, v25, v26
	v_mul_f32_e32 v26, v17, v17
	v_fmac_f32_e32 v26, v16, v16
	v_add_f32_e32 v25, v25, v26
	v_mul_f32_e32 v26, v19, v19
	v_fmac_f32_e32 v26, v18, v18
	v_add_f32_e32 v25, v26, v25
	v_add_f32_e32 v26, v24, v25
	ds_bpermute_b32 v27, v128, v26
	v_cvt_pk_bf16_f32 v24, v20, v21
	v_cvt_pk_bf16_f32 v25, v22, v23
	s_waitcnt lgkmcnt(0)
	v_add_f32_e32 v20, v26, v27
	ds_bpermute_b32 v21, v129, v20
	v_cvt_pk_bf16_f32 v26, v16, v17
	v_lshl_add_u64 v[16:17], v[160:161], 1, v[42:43]
	v_cvt_pk_bf16_f32 v27, v18, v19
	global_store_dwordx4 v[16:17], v[24:27], off sc1
	s_and_saveexec_b64 s[14:15], s[10:11]
	s_cbranch_execz .LBB0_805
	v_lshl_add_u64 v[16:17], v[40:41], 2, s[40:41]
	s_waitcnt lgkmcnt(0)
	v_add_f32_e32 v18, v20, v21
	global_atomic_add_f32 v[16:17], v18, off

; __device__ __forceinline__ unsigned cvt_pk_bf16(float lo, float hi) { unsigned r; asm volatile("v_cvt_pk_bf16_f32 %0, %1, %2" : "=v"(r) : "v"(lo), "v"(hi)); return r; }
; __device__ __forceinline__ float bf2f(unsigned b) { return __uint_as_float(b << 16); }
;     __device__ __forceinline__ void operator()(const f32x4 (&acc)[2][2][4][2], const Unit& u, int wr, int wc, int fr, int fq) const {
;     ...
;                     const int col0 = u.pn * 256 + bj * 128 + wc * 32 + fq * 8;
;                     f32x4 x0 = (f32x4){0.f, 0.f, 0.f, 0.f}, x1 = x0;
;                     if (recon) {
;                         const v4u xb = __builtin_nontemporal_load((const v4u*)(XN + (size_t)row * D + col0));
;                         x0 = (f32x4){bf2f(xb.x & 0xffffu), bf2f(xb.x >> 16), bf2f(xb.y & 0xffffu), bf2f(xb.y >> 16)} * gi[bj][0] * ri;
;                         x1 = (f32x4){bf2f(xb.z & 0xffffu), bf2f(xb.z >> 16), bf2f(xb.w & 0xffffu), bf2f(xb.w >> 16)} * gi[bj][1] * ri;
;                     } else if (valid) { x0 = *(const f32x4*)(xr + col0); x1 = *(const f32x4*)(xr + col0 + 4); }
;                     const f32x4 v0 = acc[ai][bj][m][0] + x0, v1 = acc[ai][bj][m][1] + x1;
;                     ss += (v0[0] * v0[0] + v0[1] * v0[1]) + (v0[2] * v0[2] + v0[3] * v0[3]) + (v1[0] * v1[0] + v1[1] * v1[1]) + (v1[2] * v1[2] + v1[3] * v1[3]);
;                     if (valid && row >= MP) { *(f32x4*)(out + (size_t)row * D + col0) = v0; *(f32x4*)(out + (size_t)row * D + col0 + 4) = v1; }
;                     v4u w; w.x = cvt_pk_bf16(v0[0], v0[1]); w.y = cvt_pk_bf16(v0[2], v0[3]); w.z = cvt_pk_bf16(v1[0], v1[1]); w.w = cvt_pk_bf16(v1[2], v1[3]);
;                     *(v4u*)(XMIDB + (size_t)row * D + col0) = w;
.LBB0_809:
	v_lshlrev_b32_e32 v144, 10, v24
	s_waitcnt vmcnt(1)
	v_pk_add_f32 v[14:15], v[14:15], v[22:23]
	v_pk_add_f32 v[12:13], v[12:13], v[20:21]
	s_waitcnt vmcnt(0)
	v_pk_add_f32 v[10:11], v[10:11], v[18:19]
	v_pk_add_f32 v[8:9], v[8:9], v[16:17]
	s_andn2_b64 vcc, exec, s[56:57]
	v_lshl_add_u64 v[30:31], v[144:145], 2, s[16:17]
	s_cbranch_vccnz .LBB0_811
	v_lshl_add_u64 v[16:17], v[150:151], 2, v[30:31]
	global_store_dwordx4 v[16:17], v[12:15], off sc1
	global_store_dwordx4 v[16:17], v[8:11], off offset:16 sc1
.LBB0_811:
	v_lshlrev_b64 v[20:21], 11, v[24:25]
	v_lshl_add_u64 v[26:27], s[26:27], 0, v[20:21]
	v_cvt_pk_bf16_f32 v16, v12, v13
	v_cvt_pk_bf16_f32 v17, v14, v15
	v_cvt_pk_bf16_f32 v18, v8, v9
	v_cvt_pk_bf16_f32 v19, v10, v11
	v_lshl_add_u64 v[20:21], v[150:151], 1, v[26:27]
	global_store_dwordx4 v[20:21], v[16:19], off sc1
	v_mov_b32_e32 v20, 0
	v_mov_b32_e32 v21, 0
	v_mov_b32_e32 v22, 0
	v_mov_b32_e32 v23, 0
	v_mov_b32_e32 v16, 0
	v_mov_b32_e32 v17, 0
	v_mov_b32_e32 v18, 0
	v_mov_b32_e32 v19, 0
	s_and_saveexec_b64 s[56:57], s[14:15]
	s_cbranch_execz .LBB0_813
	v_lshl_add_u64 v[16:17], v[150:151], 2, v[28:29]
	global_load_dwordx4 v[20:23], v[16:17], off offset:512
	s_nop 0
	global_load_dwordx4 v[16:19], v[16:17], off offset:528

; __device__ __forceinline__ unsigned cvt_pk_bf16(float lo, float hi) { unsigned r; asm volatile("v_cvt_pk_bf16_f32 %0, %1, %2" : "=v"(r) : "v"(lo), "v"(hi)); return r; }
;     __device__ __forceinline__ void operator()(const f32x4 (&acc)[2][2][4][2], const Unit& u, int wr, int wc, int fr, int fq) const {
;     ...
;                     const f32x4 v0 = acc[ai][bj][m][0] + x0, v1 = acc[ai][bj][m][1] + x1;
;                     ss += (v0[0] * v0[0] + v0[1] * v0[1]) + (v0[2] * v0[2] + v0[3] * v0[3]) + (v1[0] * v1[0] + v1[1] * v1[1]) + (v1[2] * v1[2] + v1[3] * v1[3]);
;                     if (valid && row >= MP) { *(f32x4*)(out + (size_t)row * D + col0) = v0; *(f32x4*)(out + (size_t)row * D + col0 + 4) = v1; }
;                     v4u w; w.x = cvt_pk_bf16(v0[0], v0[1]); w.y = cvt_pk_bf16(v0[2], v0[3]); w.z = cvt_pk_bf16(v1[0], v1[1]); w.w = cvt_pk_bf16(v1[2], v1[3]);
;                     *(v4u*)(XMIDB + (size_t)row * D + col0) = w;
;                 }
;                 ss += __shfl_xor(ss, 16); ss += __shfl_xor(ss, 32);
;                 if (fq == 0) atomicAdd(SS + row, ss);
;     __device__ __forceinline__ void done(const Unit& u) const {
;         if (done_pm == -2 || (done_pm >= 0 && u.pm != done_pm)) return;
;         asm volatile("s_waitcnt vmcnt(0)" ::: "memory");
;         asm volatile("" ::: "memory"); __builtin_amdgcn_s_barrier(); asm volatile("" ::: "memory");
;         if (threadIdx.x < 64) {
;             if (done_rel) { __builtin_amdgcn_fence(__ATOMIC_RELEASE, "agent"); asm volatile("s_waitcnt vmcnt(0)" ::: "memory"); }
;             if (threadIdx.x == 0) __hip_atomic_fetch_add(done_ctr, 1u, __ATOMIC_RELAXED, __HIP_MEMORY_SCOPE_AGENT);
;         }
.LBB0_815:
	s_waitcnt vmcnt(1)
	v_pk_add_f32 v[6:7], v[6:7], v[22:23]
	v_pk_add_f32 v[4:5], v[4:5], v[20:21]
	s_waitcnt vmcnt(0)
	v_pk_add_f32 v[2:3], v[2:3], v[18:19]
	s_andn2_b64 vcc, exec, s[12:13]
	v_pk_add_f32 v[0:1], v[0:1], v[16:17]
	s_cbranch_vccnz .LBB0_817
	v_lshl_add_u64 v[16:17], v[150:151], 2, v[30:31]
	global_store_dwordx4 v[16:17], v[4:7], off offset:512 sc1
	global_store_dwordx4 v[16:17], v[0:3], off offset:528 sc1
.LBB0_817:
	v_mul_f32_e32 v13, v13, v13
	v_fmac_f32_e32 v13, v12, v12
	v_mul_f32_e32 v12, v15, v15
	v_fmac_f32_e32 v12, v14, v14
	v_mul_f32_e32 v9, v9, v9
	v_add_f32_e32 v12, v13, v12
	v_fmac_f32_e32 v9, v8, v8
	v_add_f32_e32 v8, v12, v9
	v_mul_f32_e32 v9, v11, v11
	v_fmac_f32_e32 v9, v10, v10
	v_add_f32_e32 v8, v9, v8
	v_mul_f32_e32 v9, v5, v5
	v_mul_f32_e32 v10, v7, v7
	v_fmac_f32_e32 v9, v4, v4
	v_fmac_f32_e32 v10, v6, v6
	v_add_f32_e32 v9, v9, v10
	v_mul_f32_e32 v10, v1, v1
	v_fmac_f32_e32 v10, v0, v0
	v_add_f32_e32 v9, v9, v10
	v_mul_f32_e32 v10, v3, v3
	v_fmac_f32_e32 v10, v2, v2
	v_add_f32_e32 v9, v10, v9
	v_add_f32_e32 v10, v8, v9
	ds_bpermute_b32 v11, v128, v10
	v_cvt_pk_bf16_f32 v8, v4, v5
	v_cvt_pk_bf16_f32 v9, v6, v7
	s_waitcnt lgkmcnt(0)
	v_add_f32_e32 v4, v10, v11
	ds_bpermute_b32 v5, v129, v4
	v_cvt_pk_bf16_f32 v10, v0, v1
	v_lshl_add_u64 v[0:1], v[160:161], 1, v[26:27]
	v_cvt_pk_bf16_f32 v11, v2, v3
	global_store_dwordx4 v[0:1], v[8:11], off sc1
	s_and_saveexec_b64 s[12:13], s[10:11]
	s_cbranch_execz .LBB0_819
	v_lshl_add_u64 v[0:1], v[24:25], 2, s[40:41]
	s_waitcnt lgkmcnt(0)
	v_add_f32_e32 v2, v4, v5
	global_atomic_add_f32 v[0:1], v2, off
.LBB0_819:
	s_or_b64 exec, exec, s[12:13]
	s_waitcnt vmcnt(0)
	s_barrier
	s_and_saveexec_b64 s[12:13], s[8:9]
	s_cbranch_execz .LBB0_823
	s_waitcnt vmcnt(0) lgkmcnt(0)
	s_waitcnt vmcnt(0)
	s_and_b64 exec, exec, s[90:91]
	s_cbranch_execz .LBB0_823
	s_mov_b64 s[14:15], exec
	v_mbcnt_lo_u32_b32 v0, s14, 0
	v_mbcnt_hi_u32_b32 v0, s15, v0
	v_cmp_eq_u32_e32 vcc, 0, v0
	s_and_b64 s[56:57], exec, vcc
	s_mov_b64 exec, s[56:57]
	s_cbranch_execz .LBB0_823
	s_bcnt1_i32_b64 s14, s[14:15]
	v_mov_b32_e32 v0, s14
	global_atomic_add v145, v0, s[18:19]

;     __device__ __forceinline__ void operator()(const f32x4 (&acc)[2][2][4][2], const Unit& u, int wr, int wc, int fr, int fq) const {
;     ...
;         const bool samp = (u.pm == 64);
; #pragma unroll
;         for (int ai = 0; ai < 2; ++ai) {
;             const int rowb = u.pm * 256 + ai * 128 + wr * 64;
;             const int blk = 4 * u.pm + 2 * ai + wr;
;             float rs[4];
; #pragma unroll
;             for (int m = 0; m < 4; ++m) rs[m] = rsqrtf(SS[rowb + 16 * m + fr] * (1.0f / D) + EPS);
; #pragma unroll
;             for (int n = 0; n < 2; ++n) {
;                 f32x4 cg[4];
; #pragma unroll
;                 for (int bj = 0; bj < 2; ++bj) {
;                     const int oc = (bj ? FF : 0) + 128 * u.pn + 32 * wc + 8 * fq + 4 * n;
;                     const int cgc = 256 * u.pn + 128 * bj + 32 * wc + 8 * fq + 4 * n;
;                     const f32x4 cw0 = *(const f32x4*)(convw + oc), cw1 = *(const f32x4*)(convw + FF2 + oc), cw2 = *(const f32x4*)(convw + 2 * FF2 + oc), cb = *(const f32x4*)(convb + oc);
;                     f32x4 v[4];
; #pragma unroll
;                     for (int m = 0; m < 4; ++m) v[m] = acc[ai][bj][m][n] * rs[m];
;                     f32x4 hv = (f32x4){0.f, 0.f, 0.f, 0.f};
;                     if (!samp) {
;                         if ((blk & 31) != 0 && fr >= 14) hv = *(const f32x4*)(HALO + (size_t)(2 * blk + fr - 14) * FF2 + cgc);
.LBB0_892:
	s_branch .Lfs_begin
	s_cmp_eq_u32 s88, 64
	s_cselect_b64 s[84:85], -1, 0
	s_cmp_lg_u32 s88, 64
	s_cselect_b64 s[14:15], -1, 0
	s_lshl_b32 s77, s88, 8
	v_readlane_b32 s13, v236, 19
	s_add_i32 s77, s77, s13
	v_or_b32_e32 v202, s77, v153
	v_ashrrev_i32_e32 v203, 31, v202
	v_lshl_add_u64 v[128:129], v[202:203], 2, s[42:43]
	global_load_dword v128, v[128:129], off
	v_or_b32_e32 v200, 16, v202
	s_lshl_b32 s75, s88, 2
	s_lshl_b32 s86, s12, 7
	v_ashrrev_i32_e32 v201, 31, v200
	v_or_b32_e32 v198, 32, v202
	s_add_i32 s75, s75, s73
	v_or_b32_e32 v174, s86, v215
	v_ashrrev_i32_e32 v199, 31, v198
	v_or_b32_e32 v196, 48, v202
	v_lshl_or_b32 v170, s12, 8, v215
	v_ashrrev_i32_e32 v197, 31, v196
	s_and_b32 s12, s75, 31
	v_ashrrev_i32_e32 v175, 31, v174
	s_cmp_lg_u32 s12, 0
	v_lshlrev_b64 v[172:173], 2, v[174:175]
	s_cselect_b64 s[12:13], -1, 0
	v_lshl_add_u64 v[176:177], s[16:17], 0, v[172:173]
	v_lshl_add_u64 v[192:193], s[58:59], 0, v[172:173]
	v_lshl_add_u64 v[194:195], s[60:61], 0, v[172:173]
	v_lshl_add_u64 v[178:179], s[18:19], 0, v[172:173]
	s_and_b64 s[90:91], s[12:13], s[10:11]
	global_load_dwordx4 v[144:147], v[176:177], off
	global_load_dwordx4 v[132:135], v[192:193], off
	global_load_dwordx4 v[148:151], v[178:179], off
	s_waitcnt vmcnt(0)
	v_fmamk_f32 v128, v128, 0x3a800000, v218
	v_cmp_gt_f32_e32 vcc, s1, v128
	v_mul_f32_e32 v129, 0x4b800000, v128
	s_nop 0
	v_cndmask_b32_e32 v128, v128, v129, vcc
	v_rsq_f32_e32 v128, v128
	s_nop 0
	v_mul_f32_e32 v129, 0x45800000, v128
	v_cndmask_b32_e32 v206, v128, v129, vcc
	v_lshl_add_u64 v[128:129], v[200:201], 2, s[42:43]
	global_load_dword v182, v[128:129], off
	v_lshl_add_u64 v[128:129], v[198:199], 2, s[42:43]
	global_load_dword v181, v[128:129], off
	v_lshl_add_u64 v[128:129], v[196:197], 2, s[42:43]
	global_load_dword v180, v[128:129], off
	v_lshl_add_u32 v128, s75, 1, v216
	v_mad_i64_i32 v[208:209], s[12:13], v128, s4, 0
	global_load_dwordx4 v[128:131], v[194:195], off
	v_pk_mul_f32 v[126:127], v[126:127], v[206:207] op_sel_hi:[1,0]
	v_pk_mul_f32 v[124:125], v[124:125], v[206:207] op_sel_hi:[1,0]
	s_mov_b64 s[12:13], -1
	s_and_b64 vcc, exec, s[84:85]
	s_cbranch_vccnz .LBB0_896
	v_mov_b32_e32 v136, 0
	v_mov_b32_e32 v137, 0
	v_mov_b32_e32 v138, 0
	v_mov_b32_e32 v139, 0
	s_and_saveexec_b64 s[12:13], s[90:91]
	s_cbranch_execz .LBB0_895
	v_lshl_add_u64 v[136:137], s[44:45], 0, v[208:209]
	v_ashrrev_i32_e32 v171, 31, v170
	v_lshl_add_u64 v[136:137], v[170:171], 2, v[136:137]
	global_load_dwordx4 v[136:139], v[136:137], off

;     __device__ __forceinline__ void done(const Unit& u) const {
;         if (done_pm == -2 || (done_pm >= 0 && u.pm != done_pm)) return;
;         asm volatile("s_waitcnt vmcnt(0)" ::: "memory");
;         asm volatile("" ::: "memory"); __builtin_amdgcn_s_barrier(); asm volatile("" ::: "memory");
;         if (threadIdx.x < 64) {
;             if (done_rel) { __builtin_amdgcn_fence(__ATOMIC_RELEASE, "agent"); asm volatile("s_waitcnt vmcnt(0)" ::: "memory"); }
;             if (threadIdx.x == 0) __hip_atomic_fetch_add(done_ctr, 1u, __ATOMIC_RELAXED, __HIP_MEMORY_SCOPE_AGENT);
;         }
.Lfs_done:
	s_waitcnt vmcnt(0)
	s_barrier
	s_and_saveexec_b64 s[12:13], s[8:9]
	s_cbranch_execz .LBB0_1113
	s_waitcnt vmcnt(0)
	s_waitcnt vmcnt(0)
	s_and_b64 exec, exec, s[90:91]
	s_cbranch_execz .LBB0_1113
	s_mov_b64 s[14:15], exec
	v_mbcnt_lo_u32_b32 v0, s14, 0
	v_mbcnt_hi_u32_b32 v0, s15, v0
	v_cmp_eq_u32_e32 vcc, 0, v0
	s_and_b64 s[56:57], exec, vcc
	s_mov_b64 exec, s[56:57]
	s_cbranch_execz .LBB0_1113
	s_bcnt1_i32_b64 s14, s[14:15]
	v_mov_b32_e32 v0, s14
	v_readlane_b32 s14, v236, 17
	v_readlane_b32 s15, v236, 18
	s_nop 4
	global_atomic_add v169, v0, s[14:15]

;     __device__ __forceinline__ void operator()(const f32x4 (&acc)[2][2][4][2], const Unit& u, int wr, int wc, int fr, int fq) const {
;     ...
;             float rs[4];
; #pragma unroll
;             for (int m = 0; m < 4; ++m) rs[m] = rsqrtf(SS[rowb + 16 * m + fr] * (1.0f / D) + EPS);
; #pragma unroll
;             for (int n = 0; n < 2; ++n) {
;                 f32x4 cg[4];
; #pragma unroll
;                 for (int bj = 0; bj < 2; ++bj) {
;                     const int oc = (bj ? FF : 0) + 128 * u.pn + 32 * wc + 8 * fq + 4 * n;
;                     const int cgc = 256 * u.pn + 128 * bj + 32 * wc + 8 * fq + 4 * n;
;                     const f32x4 cw0 = *(const f32x4*)(convw + oc), cw1 = *(const f32x4*)(convw + FF2 + oc), cw2 = *(const f32x4*)(convw + 2 * FF2 + oc), cb = *(const f32x4*)(convb + oc);
;                     f32x4 v[4];
; #pragma unroll
;                     for (int m = 0; m < 4; ++m) v[m] = acc[ai][bj][m][n] * rs[m];
;                     f32x4 hv = (f32x4){0.f, 0.f, 0.f, 0.f};
;                     if (!samp) {
;                         if ((blk & 31) != 0 && fr >= 14) hv = *(const f32x4*)(HALO + (size_t)(2 * blk + fr - 14) * FF2 + cgc);
;                         if ((u.pm & 7) == 7 && ai == 1 && wr == 1 && fr >= 14) *(f32x4*)(ncp + (size_t)((u.pm >> 3) * 2 + (fr - 14)) * FF2 + oc) = v[3];
;                     }
; #pragma unroll
;                     for (int m = 0; m < 4; ++m) {
;                         f32x4 cv;
;                         if (!samp) {
;                             const f32x4 prev = m ? v[m - 1] : hv;
; #pragma unroll
;                             for (int e = 0; e < 4; ++e) {
;                                 const int vi = __float_as_int(v[m][e]), pi = __float_as_int(prev[e]);
;                                 const int o1 = __builtin_amdgcn_mov_dpp(pi, 0x121, 0xf, 0xf, false);
;                                 const int o2 = __builtin_amdgcn_mov_dpp(pi, 0x122, 0xf, 0xf, false);
;                                 const float p1 = __int_as_float(__builtin_amdgcn_update_dpp(o1, vi, 0x111, 0xf, 0xf, false));
;                                 const float p2 = __int_as_float(__builtin_amdgcn_update_dpp(o2, vi, 0x112, 0xf, 0xf, false));
;                                 cv[e] = cb[e] + cw0[e] * p2 + cw1[e] * p1 + cw2[e] * v[m][e];
;                             }
;                         } else {
.Lfs_begin:
	v_readlane_b32 s13, v236, 19
	s_lshl_b32 s89, s12, 7
	s_nop 0
	v_add_u32_e32 v246, s13, v153
	v_lshlrev_b32_e32 v247, 2, v246
	v_add_u32_e32 v247, 0x10000, v247
	global_load_dword v238, v247, s[42:43]
	global_load_dword v239, v247, s[42:43] offset:64
	global_load_dword v240, v247, s[42:43] offset:128
	global_load_dword v241, v247, s[42:43] offset:192
	v_add_u32_e32 v248, s89, v215
	v_lshlrev_b32_e32 v237, 2, v248
	v_add_u32_e32 v250, 0x2c00, v237
	global_load_dwordx4 v[170:173], v237, s[16:17]
	global_load_dwordx4 v[174:177], v237, s[16:17] offset:16
	global_load_dwordx4 v[178:181], v250, s[16:17]
	global_load_dwordx4 v[182:185], v250, s[16:17] offset:16
	global_load_dwordx4 v[186:189], v237, s[58:59]
	global_load_dwordx4 v[190:193], v237, s[58:59] offset:16
	global_load_dwordx4 v[194:197], v250, s[58:59]
	global_load_dwordx4 v[198:201], v250, s[58:59] offset:16
	global_load_dwordx4 v[202:205], v237, s[60:61]
	global_load_dwordx4 v[206:209], v237, s[60:61] offset:16
	global_load_dwordx4 v[210:213], v250, s[60:61]
	global_load_dwordx4 v[128:131], v250, s[60:61] offset:16
	global_load_dwordx4 v[132:135], v237, s[18:19]
	global_load_dwordx4 v[136:139], v237, s[18:19] offset:16
	global_load_dwordx4 v[140:143], v250, s[18:19]
	global_load_dwordx4 v[144:147], v250, s[18:19] offset:16
	v_add_u32_e32 v249, 0x4000, v246
	v_mul_u32_u24_e32 v151, 0x1600, v249
	v_lshl_add_u32 v151, v248, 1, v151
	v_mov_b32_e32 v219, s64
	v_mul_u32_u24_e32 v150, 0xb000, v246
	v_add_u32_e32 v150, v150, v237
	global_load_dwordx4 v[0:3], v150, s[20:21]
	global_load_dwordx4 v[4:7], v150, s[20:21] offset:16
	s_add_u32 s56, s20, 0x2c00
	s_addc_u32 s57, s21, 0
	global_load_dwordx4 v[8:11], v150, s[56:57]
	global_load_dwordx4 v[12:15], v150, s[56:57] offset:16
	s_add_u32 s56, s20, 0x5800
	s_addc_u32 s57, s21, 0
	global_load_dwordx4 v[16:19], v150, s[56:57]
	global_load_dwordx4 v[20:23], v150, s[56:57] offset:16
	s_add_u32 s56, s20, 0x8400
	s_addc_u32 s57, s21, 0
	global_load_dwordx4 v[24:27], v150, s[56:57]
	global_load_dwordx4 v[28:31], v150, s[56:57] offset:16
	s_add_u32 s14, s20, 0xb0000
	s_addc_u32 s15, s21, 0
	global_load_dwordx4 v[32:35], v150, s[14:15]
	global_load_dwordx4 v[36:39], v150, s[14:15] offset:16
	s_add_u32 s56, s14, 0x2c00
	s_addc_u32 s57, s15, 0
	global_load_dwordx4 v[40:43], v150, s[56:57]
	global_load_dwordx4 v[44:47], v150, s[56:57] offset:16
	s_add_u32 s56, s14, 0x5800
	s_addc_u32 s57, s15, 0
	global_load_dwordx4 v[48:51], v150, s[56:57]
	global_load_dwordx4 v[52:55], v150, s[56:57] offset:16
	s_add_u32 s56, s14, 0x8400
	s_addc_u32 s57, s15, 0
	global_load_dwordx4 v[56:59], v150, s[56:57]
	global_load_dwordx4 v[60:63], v150, s[56:57] offset:16
	s_waitcnt vmcnt(32)
	v_fmamk_f32 v238, v238, 0x3a800000, v218
	v_fmamk_f32 v239, v239, 0x3a800000, v218
	v_fmamk_f32 v240, v240, 0x3a800000, v218
	v_fmamk_f32 v241, v241, 0x3a800000, v218
	v_rsq_f32_e32 v238, v238
	v_rsq_f32_e32 v239, v239
	v_rsq_f32_e32 v240, v240
	v_rsq_f32_e32 v241, v241
	s_nop 0
	v_pk_mul_f32 v[124:125], v[124:125], v[238:239] op_sel_hi:[1,0]
	v_pk_mul_f32 v[126:127], v[126:127], v[238:239] op_sel_hi:[1,0]
	v_pk_mul_f32 v[92:93], v[92:93], v[238:239] op_sel_hi:[1,0]
	v_pk_mul_f32 v[94:95], v[94:95], v[238:239] op_sel_hi:[1,0]
	v_pk_mul_f32 v[108:109], v[108:109], v[238:239] op_sel_hi:[1,0]
	v_pk_mul_f32 v[110:111], v[110:111], v[238:239] op_sel_hi:[1,0]
	v_pk_mul_f32 v[76:77], v[76:77], v[238:239] op_sel_hi:[1,0]
	v_pk_mul_f32 v[78:79], v[78:79], v[238:239] op_sel_hi:[1,0]
	v_pk_mul_f32 v[120:121], v[120:121], v[238:239] op_sel:[0,1] op_sel_hi:[1,1]
	v_pk_mul_f32 v[122:123], v[122:123], v[238:239] op_sel:[0,1] op_sel_hi:[1,1]
	v_pk_mul_f32 v[88:89], v[88:89], v[238:239] op_sel:[0,1] op_sel_hi:[1,1]
	v_pk_mul_f32 v[90:91], v[90:91], v[238:239] op_sel:[0,1] op_sel_hi:[1,1]
	v_pk_mul_f32 v[104:105], v[104:105], v[238:239] op_sel:[0,1] op_sel_hi:[1,1]
	v_pk_mul_f32 v[106:107], v[106:107], v[238:239] op_sel:[0,1] op_sel_hi:[1,1]
	v_pk_mul_f32 v[72:73], v[72:73], v[238:239] op_sel:[0,1] op_sel_hi:[1,1]
	v_pk_mul_f32 v[74:75], v[74:75], v[238:239] op_sel:[0,1] op_sel_hi:[1,1]
	v_pk_mul_f32 v[116:117], v[116:117], v[240:241] op_sel_hi:[1,0]
	v_pk_mul_f32 v[118:119], v[118:119], v[240:241] op_sel_hi:[1,0]
	v_pk_mul_f32 v[84:85], v[84:85], v[240:241] op_sel_hi:[1,0]
	v_pk_mul_f32 v[86:87], v[86:87], v[240:241] op_sel_hi:[1,0]
	v_pk_mul_f32 v[100:101], v[100:101], v[240:241] op_sel_hi:[1,0]
	v_pk_mul_f32 v[102:103], v[102:103], v[240:241] op_sel_hi:[1,0]
	v_pk_mul_f32 v[68:69], v[68:69], v[240:241] op_sel_hi:[1,0]
	v_pk_mul_f32 v[70:71], v[70:71], v[240:241] op_sel_hi:[1,0]
	v_pk_mul_f32 v[112:113], v[112:113], v[240:241] op_sel:[0,1] op_sel_hi:[1,1]
	v_pk_mul_f32 v[114:115], v[114:115], v[240:241] op_sel:[0,1] op_sel_hi:[1,1]
	v_pk_mul_f32 v[80:81], v[80:81], v[240:241] op_sel:[0,1] op_sel_hi:[1,1]
	v_pk_mul_f32 v[82:83], v[82:83], v[240:241] op_sel:[0,1] op_sel_hi:[1,1]
	v_pk_mul_f32 v[96:97], v[96:97], v[240:241] op_sel:[0,1] op_sel_hi:[1,1]
	v_pk_mul_f32 v[98:99], v[98:99], v[240:241] op_sel:[0,1] op_sel_hi:[1,1]
	v_pk_mul_f32 v[64:65], v[64:65], v[240:241] op_sel:[0,1] op_sel_hi:[1,1]
	v_pk_mul_f32 v[66:67], v[66:67], v[240:241] op_sel:[0,1] op_sel_hi:[1,1]
	s_waitcnt vmcnt(8)
; __device__ __forceinline__ f32x2 gelu_pk(f32x2 v) {
;     const f32x2 av = __builtin_elementwise_abs(v), d = av * 0.2316418882f + 1.0f;
;     f32x2 t; t.x = __builtin_amdgcn_rcpf(d.x); t.y = __builtin_amdgcn_rcpf(d.y);
;     __device__ __forceinline__ void operator()(const f32x4 (&acc)[2][2][4][2], const Unit& u, int wr, int wc, int fr, int fq) const {
;     ...
;                     for (int m = 0; m < 4; ++m) {
;                         f32x4 cv;
;                         if (!samp) {
;                             const f32x4 prev = m ? v[m - 1] : hv;
; #pragma unroll
;                             for (int e = 0; e < 4; ++e) {
;                                 const int vi = __float_as_int(v[m][e]), pi = __float_as_int(prev[e]);
;                                 const int o1 = __builtin_amdgcn_mov_dpp(pi, 0x121, 0xf, 0xf, false);
;                                 const int o2 = __builtin_amdgcn_mov_dpp(pi, 0x122, 0xf, 0xf, false);
;                                 const float p1 = __int_as_float(__builtin_amdgcn_update_dpp(o1, vi, 0x111, 0xf, 0xf, false));
;                                 const float p2 = __int_as_float(__builtin_amdgcn_update_dpp(o2, vi, 0x112, 0xf, 0xf, false));
;                                 cv[e] = cb[e] + cw0[e] * p2 + cw1[e] * p1 + cw2[e] * v[m][e];
;                             }
;                         } else {
;                             const int ns = rowb + 16 * m + fr - MP;
;                             f32x4 s0 = (f32x4){0.f, 0.f, 0.f, 0.f}, s1 = s0;
;                             if (ns < NS) {
;                                 s0 = *(const f32x4*)(state + (size_t)(ns * 2 + 0) * FF2 + oc); s1 = *(const f32x4*)(state + (size_t)(ns * 2 + 1) * FF2 + oc);
;                                 *(f32x4*)(ncs + (size_t)(ns * 2 + 0) * FF2 + oc) = s1; *(f32x4*)(ncs + (size_t)(ns * 2 + 1) * FF2 + oc) = v[m];
;                             }
;                             cv = cb + cw0 * s0 + cw1 * s1 + cw2 * v[m];
;                         }
;                         if (bj == 0) cg[m] = gelu4(cv);
;                         else {
;                             const f32x4 r = cg[m] * cv;
;                             v2u w; w.x = cvt_pk_bf16(r[0], r[1]); w.y = cvt_pk_bf16(r[2], r[3]);
;                             *(v2u*)(ACT + (size_t)(rowb + 16 * m + fr) * FF + 128 * u.pn + 32 * wc + 8 * fq + 4 * n) = w;
;                         }
	v_pk_fma_f32 v[254:255], v[170:171], v[0:1], v[132:133]
	v_pk_fma_f32 v[148:149], v[172:173], v[2:3], v[134:135]
	v_pk_fma_f32 v[254:255], v[186:187], v[16:17], v[254:255]
	v_pk_fma_f32 v[148:149], v[188:189], v[18:19], v[148:149]
	v_pk_fma_f32 v[254:255], v[202:203], v[124:125], v[254:255]
	v_pk_fma_f32 v[148:149], v[204:205], v[126:127], v[148:149]
	v_fma_f32 v246, |v254|, s38, 1.0
	v_fma_f32 v247, |v255|, s38, 1.0
	v_fma_f32 v248, |v148|, s38, 1.0
	v_fma_f32 v249, |v149|, s38, 1.0
	v_mul_f32_e32 v250, v254, v254
	v_mul_f32_e32 v251, v255, v255
	v_mul_f32_e32 v252, v148, v148
	v_mul_f32_e32 v253, v149, v149
	v_rcp_f32_e32 v246, v246
	v_rcp_f32_e32 v247, v247
	v_rcp_f32_e32 v248, v248
	v_rcp_f32_e32 v249, v249
	v_mul_f32_e32 v250, s72, v250
	v_mul_f32_e32 v251, s72, v251
	v_mul_f32_e32 v252, s72, v252
	v_mul_f32_e32 v253, s72, v253
	v_exp_f32_e32 v250, v250
	v_exp_f32_e32 v251, v251
	v_exp_f32_e32 v252, v252
	v_exp_f32_e32 v253, v253
	v_fmamk_f32 v238, v246, 0x3f07dc22, v219
	v_fmamk_f32 v239, v247, 0x3f07dc22, v219
	v_fmamk_f32 v240, v248, 0x3f07dc22, v219
	v_fmamk_f32 v241, v249, 0x3f07dc22, v219
	v_fma_f32 v238, v246, v238, s66
	v_fma_f32 v239, v247, v239, s66
	v_fma_f32 v240, v248, v240, s66
	v_fma_f32 v241, v249, v241, s66
	v_fma_f32 v238, v246, v238, s68
	v_fma_f32 v239, v247, v239, s68
	v_fma_f32 v240, v248, v240, s68
	v_fma_f32 v241, v249, v241, s68
	v_fma_f32 v238, v246, v238, s70
	v_fma_f32 v239, v247, v239, s70
	v_fma_f32 v240, v248, v240, s70
	v_fma_f32 v241, v249, v241, s70
	v_mul_f32_e32 v238, v246, v238
	v_mul_f32_e32 v239, v247, v239
	v_mul_f32_e32 v240, v248, v240
	v_mul_f32_e32 v241, v249, v241
	v_mul_f32_e32 v238, v250, v238
	v_mul_f32_e32 v239, v251, v239
	v_mul_f32_e32 v240, v252, v240
	v_mul_f32_e32 v241, v253, v241
	v_max_f32_e32 v246, 0, v254
	v_max_f32_e32 v247, 0, v255
	v_max_f32_e32 v248, 0, v148
	v_max_f32_e32 v249, 0, v149
	v_fma_f32 v238, -|v254|, v238, v246
	v_fma_f32 v239, -|v255|, v239, v247
	v_fma_f32 v240, -|v148|, v240, v248
	v_fma_f32 v241, -|v149|, v241, v249
	v_pk_fma_f32 v[254:255], v[178:179], v[8:9], v[140:141]
	v_pk_fma_f32 v[148:149], v[180:181], v[10:11], v[142:143]
	v_pk_fma_f32 v[254:255], v[194:195], v[24:25], v[254:255]
	v_pk_fma_f32 v[148:149], v[196:197], v[26:27], v[148:149]
	v_pk_fma_f32 v[254:255], v[210:211], v[108:109], v[254:255]
	v_pk_fma_f32 v[148:149], v[212:213], v[110:111], v[148:149]
	v_pk_mul_f32 v[254:255], v[238:239], v[254:255]
	v_pk_mul_f32 v[148:149], v[240:241], v[148:149]
	v_cvt_pk_bf16_f32 v242, v254, v255
	v_cvt_pk_bf16_f32 v243, v148, v149
	v_pk_fma_f32 v[254:255], v[174:175], v[4:5], v[136:137]
	v_pk_fma_f32 v[148:149], v[176:177], v[6:7], v[138:139]
	v_pk_fma_f32 v[254:255], v[190:191], v[20:21], v[254:255]
	v_pk_fma_f32 v[148:149], v[192:193], v[22:23], v[148:149]
	v_pk_fma_f32 v[254:255], v[206:207], v[92:93], v[254:255]
	v_pk_fma_f32 v[148:149], v[208:209], v[94:95], v[148:149]
	v_fma_f32 v246, |v254|, s38, 1.0
	v_fma_f32 v247, |v255|, s38, 1.0
	v_fma_f32 v248, |v148|, s38, 1.0
	v_fma_f32 v249, |v149|, s38, 1.0
	v_mul_f32_e32 v250, v254, v254
	v_mul_f32_e32 v251, v255, v255
	v_mul_f32_e32 v252, v148, v148
	v_mul_f32_e32 v253, v149, v149
	v_rcp_f32_e32 v246, v246
	v_rcp_f32_e32 v247, v247
	v_rcp_f32_e32 v248, v248
	v_rcp_f32_e32 v249, v249
	v_mul_f32_e32 v250, s72, v250
	v_mul_f32_e32 v251, s72, v251
	v_mul_f32_e32 v252, s72, v252
	v_mul_f32_e32 v253, s72, v253
	v_exp_f32_e32 v250, v250
	v_exp_f32_e32 v251, v251
	v_exp_f32_e32 v252, v252
	v_exp_f32_e32 v253, v253
	v_fmamk_f32 v238, v246, 0x3f07dc22, v219
	v_fmamk_f32 v239, v247, 0x3f07dc22, v219
	v_fmamk_f32 v240, v248, 0x3f07dc22, v219
	v_fmamk_f32 v241, v249, 0x3f07dc22, v219
	v_fma_f32 v238, v246, v238, s66
	v_fma_f32 v239, v247, v239, s66
	v_fma_f32 v240, v248, v240, s66
	v_fma_f32 v241, v249, v241, s66
	v_fma_f32 v238, v246, v238, s68
	v_fma_f32 v239, v247, v239, s68
	v_fma_f32 v240, v248, v240, s68
	v_fma_f32 v241, v249, v241, s68
	v_fma_f32 v238, v246, v238, s70
	v_fma_f32 v239, v247, v239, s70
	v_fma_f32 v240, v248, v240, s70
	v_fma_f32 v241, v249, v241, s70
	v_mul_f32_e32 v238, v246, v238
	v_mul_f32_e32 v239, v247, v239
	v_mul_f32_e32 v240, v248, v240
	v_mul_f32_e32 v241, v249, v241
	v_mul_f32_e32 v238, v250, v238
	v_mul_f32_e32 v239, v251, v239
	v_mul_f32_e32 v240, v252, v240
	v_mul_f32_e32 v241, v253, v241
	v_max_f32_e32 v246, 0, v254
	v_max_f32_e32 v247, 0, v255
	v_max_f32_e32 v248, 0, v148
	v_max_f32_e32 v249, 0, v149
	v_fma_f32 v238, -|v254|, v238, v246
	v_fma_f32 v239, -|v255|, v239, v247
	v_fma_f32 v240, -|v148|, v240, v248
	v_fma_f32 v241, -|v149|, v241, v249
	v_pk_fma_f32 v[254:255], v[182:183], v[12:13], v[144:145]
	v_pk_fma_f32 v[148:149], v[184:185], v[14:15], v[146:147]
	v_pk_fma_f32 v[254:255], v[198:199], v[28:29], v[254:255]
	v_pk_fma_f32 v[148:149], v[200:201], v[30:31], v[148:149]
	v_pk_fma_f32 v[254:255], v[128:129], v[76:77], v[254:255]
	v_pk_fma_f32 v[148:149], v[130:131], v[78:79], v[148:149]
	v_pk_mul_f32 v[254:255], v[238:239], v[254:255]
	v_pk_mul_f32 v[148:149], v[240:241], v[148:149]
	v_cvt_pk_bf16_f32 v244, v254, v255
	v_cvt_pk_bf16_f32 v245, v148, v149
	global_store_dwordx4 v151, v[242:245], s[46:47] sc1
	global_store_dwordx4 v150, v[16:19], s[52:53]
	global_store_dwordx4 v150, v[20:23], s[52:53] offset:16
	s_add_u32 s56, s52, 0x5800
	s_addc_u32 s57, s53, 0
	global_store_dwordx4 v150, v[124:127], s[56:57]
	global_store_dwordx4 v150, v[92:95], s[56:57] offset:16
	s_add_u32 s56, s52, 0x2c00
	s_addc_u32 s57, s53, 0
	global_store_dwordx4 v150, v[24:27], s[56:57]
	global_store_dwordx4 v150, v[28:31], s[56:57] offset:16
	s_add_u32 s56, s52, 0x8400
	s_addc_u32 s57, s53, 0
	global_store_dwordx4 v150, v[108:111], s[56:57]
	global_store_dwordx4 v150, v[76:79], s[56:57] offset:16
	s_add_u32 s14, s20, 0x160000
	s_addc_u32 s15, s21, 0
	global_load_dwordx4 v[0:3], v150, s[14:15]
	global_load_dwordx4 v[4:7], v150, s[14:15] offset:16
	s_add_u32 s56, s14, 0x2c00
	s_addc_u32 s57, s15, 0
	global_load_dwordx4 v[8:11], v150, s[56:57]
	global_load_dwordx4 v[12:15], v150, s[56:57] offset:16
	s_add_u32 s56, s14, 0x5800
	s_addc_u32 s57, s15, 0
	global_load_dwordx4 v[16:19], v150, s[56:57]
	global_load_dwordx4 v[20:23], v150, s[56:57] offset:16
	s_add_u32 s56, s14, 0x8400
	s_addc_u32 s57, s15, 0
	global_load_dwordx4 v[24:27], v150, s[56:57]
	global_load_dwordx4 v[28:31], v150, s[56:57] offset:16
	s_waitcnt vmcnt(17)
; __device__ __forceinline__ f32x2 gelu_pk(f32x2 v) {
;     const f32x2 av = __builtin_elementwise_abs(v), d = av * 0.2316418882f + 1.0f;
;     f32x2 t; t.x = __builtin_amdgcn_rcpf(d.x); t.y = __builtin_amdgcn_rcpf(d.y);
;     __device__ __forceinline__ void operator()(const f32x4 (&acc)[2][2][4][2], const Unit& u, int wr, int wc, int fr, int fq) const {
;     ...
;                     for (int m = 0; m < 4; ++m) {
;                         f32x4 cv;
;                         if (!samp) {
;                             const f32x4 prev = m ? v[m - 1] : hv;
; #pragma unroll
;                             for (int e = 0; e < 4; ++e) {
;                                 const int vi = __float_as_int(v[m][e]), pi = __float_as_int(prev[e]);
;                                 const int o1 = __builtin_amdgcn_mov_dpp(pi, 0x121, 0xf, 0xf, false);
;                                 const int o2 = __builtin_amdgcn_mov_dpp(pi, 0x122, 0xf, 0xf, false);
;                                 const float p1 = __int_as_float(__builtin_amdgcn_update_dpp(o1, vi, 0x111, 0xf, 0xf, false));
;                                 const float p2 = __int_as_float(__builtin_amdgcn_update_dpp(o2, vi, 0x112, 0xf, 0xf, false));
;                                 cv[e] = cb[e] + cw0[e] * p2 + cw1[e] * p1 + cw2[e] * v[m][e];
;                             }
;                         } else {
;                             const int ns = rowb + 16 * m + fr - MP;
;                             f32x4 s0 = (f32x4){0.f, 0.f, 0.f, 0.f}, s1 = s0;
;                             if (ns < NS) {
;                                 s0 = *(const f32x4*)(state + (size_t)(ns * 2 + 0) * FF2 + oc); s1 = *(const f32x4*)(state + (size_t)(ns * 2 + 1) * FF2 + oc);
;                                 *(f32x4*)(ncs + (size_t)(ns * 2 + 0) * FF2 + oc) = s1; *(f32x4*)(ncs + (size_t)(ns * 2 + 1) * FF2 + oc) = v[m];
;                             }
;                             cv = cb + cw0 * s0 + cw1 * s1 + cw2 * v[m];
;                         }
;                         if (bj == 0) cg[m] = gelu4(cv);
;                         else {
;                             const f32x4 r = cg[m] * cv;
;                             v2u w; w.x = cvt_pk_bf16(r[0], r[1]); w.y = cvt_pk_bf16(r[2], r[3]);
;                             *(v2u*)(ACT + (size_t)(rowb + 16 * m + fr) * FF + 128 * u.pn + 32 * wc + 8 * fq + 4 * n) = w;
;                         }
	v_pk_fma_f32 v[254:255], v[170:171], v[32:33], v[132:133]
	v_pk_fma_f32 v[148:149], v[172:173], v[34:35], v[134:135]
	v_pk_fma_f32 v[254:255], v[186:187], v[48:49], v[254:255]
	v_pk_fma_f32 v[148:149], v[188:189], v[50:51], v[148:149]
	v_pk_fma_f32 v[254:255], v[202:203], v[120:121], v[254:255]
	v_pk_fma_f32 v[148:149], v[204:205], v[122:123], v[148:149]
	v_fma_f32 v246, |v254|, s38, 1.0
	v_fma_f32 v247, |v255|, s38, 1.0
	v_fma_f32 v248, |v148|, s38, 1.0
	v_fma_f32 v249, |v149|, s38, 1.0
	v_mul_f32_e32 v250, v254, v254
	v_mul_f32_e32 v251, v255, v255
	v_mul_f32_e32 v252, v148, v148
	v_mul_f32_e32 v253, v149, v149
	v_rcp_f32_e32 v246, v246
	v_rcp_f32_e32 v247, v247
	v_rcp_f32_e32 v248, v248
	v_rcp_f32_e32 v249, v249
	v_mul_f32_e32 v250, s72, v250
	v_mul_f32_e32 v251, s72, v251
	v_mul_f32_e32 v252, s72, v252
	v_mul_f32_e32 v253, s72, v253
	v_exp_f32_e32 v250, v250
	v_exp_f32_e32 v251, v251
	v_exp_f32_e32 v252, v252
	v_exp_f32_e32 v253, v253
	v_fmamk_f32 v238, v246, 0x3f07dc22, v219
	v_fmamk_f32 v239, v247, 0x3f07dc22, v219
	v_fmamk_f32 v240, v248, 0x3f07dc22, v219
	v_fmamk_f32 v241, v249, 0x3f07dc22, v219
	v_fma_f32 v238, v246, v238, s66
	v_fma_f32 v239, v247, v239, s66
	v_fma_f32 v240, v248, v240, s66
	v_fma_f32 v241, v249, v241, s66
	v_fma_f32 v238, v246, v238, s68
	v_fma_f32 v239, v247, v239, s68
	v_fma_f32 v240, v248, v240, s68
	v_fma_f32 v241, v249, v241, s68
	v_fma_f32 v238, v246, v238, s70
	v_fma_f32 v239, v247, v239, s70
	v_fma_f32 v240, v248, v240, s70
	v_fma_f32 v241, v249, v241, s70
	v_mul_f32_e32 v238, v246, v238
	v_mul_f32_e32 v239, v247, v239
	v_mul_f32_e32 v240, v248, v240
	v_mul_f32_e32 v241, v249, v241
	v_mul_f32_e32 v238, v250, v238
	v_mul_f32_e32 v239, v251, v239
	v_mul_f32_e32 v240, v252, v240
	v_mul_f32_e32 v241, v253, v241
	v_max_f32_e32 v246, 0, v254
	v_max_f32_e32 v247, 0, v255
	v_max_f32_e32 v248, 0, v148
	v_max_f32_e32 v249, 0, v149
	v_fma_f32 v238, -|v254|, v238, v246
	v_fma_f32 v239, -|v255|, v239, v247
	v_fma_f32 v240, -|v148|, v240, v248
	v_fma_f32 v241, -|v149|, v241, v249
	v_pk_fma_f32 v[254:255], v[178:179], v[40:41], v[140:141]
	v_pk_fma_f32 v[148:149], v[180:181], v[42:43], v[142:143]
	v_pk_fma_f32 v[254:255], v[194:195], v[56:57], v[254:255]
	v_pk_fma_f32 v[148:149], v[196:197], v[58:59], v[148:149]
	v_pk_fma_f32 v[254:255], v[210:211], v[104:105], v[254:255]
	v_pk_fma_f32 v[148:149], v[212:213], v[106:107], v[148:149]
	v_pk_mul_f32 v[254:255], v[238:239], v[254:255]
	v_pk_mul_f32 v[148:149], v[240:241], v[148:149]
	v_cvt_pk_bf16_f32 v242, v254, v255
	v_cvt_pk_bf16_f32 v243, v148, v149
	v_pk_fma_f32 v[254:255], v[174:175], v[36:37], v[136:137]
	v_pk_fma_f32 v[148:149], v[176:177], v[38:39], v[138:139]
	v_pk_fma_f32 v[254:255], v[190:191], v[52:53], v[254:255]
	v_pk_fma_f32 v[148:149], v[192:193], v[54:55], v[148:149]
	v_pk_fma_f32 v[254:255], v[206:207], v[88:89], v[254:255]
	v_pk_fma_f32 v[148:149], v[208:209], v[90:91], v[148:149]
	v_fma_f32 v246, |v254|, s38, 1.0
	v_fma_f32 v247, |v255|, s38, 1.0
	v_fma_f32 v248, |v148|, s38, 1.0
	v_fma_f32 v249, |v149|, s38, 1.0
	v_mul_f32_e32 v250, v254, v254
	v_mul_f32_e32 v251, v255, v255
	v_mul_f32_e32 v252, v148, v148
	v_mul_f32_e32 v253, v149, v149
	v_rcp_f32_e32 v246, v246
	v_rcp_f32_e32 v247, v247
	v_rcp_f32_e32 v248, v248
	v_rcp_f32_e32 v249, v249
	v_mul_f32_e32 v250, s72, v250
	v_mul_f32_e32 v251, s72, v251
	v_mul_f32_e32 v252, s72, v252
	v_mul_f32_e32 v253, s72, v253
	v_exp_f32_e32 v250, v250
	v_exp_f32_e32 v251, v251
	v_exp_f32_e32 v252, v252
	v_exp_f32_e32 v253, v253
	v_fmamk_f32 v238, v246, 0x3f07dc22, v219
	v_fmamk_f32 v239, v247, 0x3f07dc22, v219
	v_fmamk_f32 v240, v248, 0x3f07dc22, v219
	v_fmamk_f32 v241, v249, 0x3f07dc22, v219
	v_fma_f32 v238, v246, v238, s66
	v_fma_f32 v239, v247, v239, s66
	v_fma_f32 v240, v248, v240, s66
	v_fma_f32 v241, v249, v241, s66
	v_fma_f32 v238, v246, v238, s68
	v_fma_f32 v239, v247, v239, s68
	v_fma_f32 v240, v248, v240, s68
	v_fma_f32 v241, v249, v241, s68
	v_fma_f32 v238, v246, v238, s70
	v_fma_f32 v239, v247, v239, s70
	v_fma_f32 v240, v248, v240, s70
	v_fma_f32 v241, v249, v241, s70
	v_mul_f32_e32 v238, v246, v238
	v_mul_f32_e32 v239, v247, v239
	v_mul_f32_e32 v240, v248, v240
	v_mul_f32_e32 v241, v249, v241
	v_mul_f32_e32 v238, v250, v238
	v_mul_f32_e32 v239, v251, v239
	v_mul_f32_e32 v240, v252, v240
	v_mul_f32_e32 v241, v253, v241
	v_max_f32_e32 v246, 0, v254
	v_max_f32_e32 v247, 0, v255
	v_max_f32_e32 v248, 0, v148
	v_max_f32_e32 v249, 0, v149
	v_fma_f32 v238, -|v254|, v238, v246
	v_fma_f32 v239, -|v255|, v239, v247
	v_fma_f32 v240, -|v148|, v240, v248
	v_fma_f32 v241, -|v149|, v241, v249
	v_pk_fma_f32 v[254:255], v[182:183], v[44:45], v[144:145]
	v_pk_fma_f32 v[148:149], v[184:185], v[46:47], v[146:147]
	v_pk_fma_f32 v[254:255], v[198:199], v[60:61], v[254:255]
	v_pk_fma_f32 v[148:149], v[200:201], v[62:63], v[148:149]
	v_pk_fma_f32 v[254:255], v[128:129], v[72:73], v[254:255]
	v_pk_fma_f32 v[148:149], v[130:131], v[74:75], v[148:149]
	v_pk_mul_f32 v[254:255], v[238:239], v[254:255]
	v_pk_mul_f32 v[148:149], v[240:241], v[148:149]
	v_cvt_pk_bf16_f32 v244, v254, v255
	v_cvt_pk_bf16_f32 v245, v148, v149
	s_add_u32 s56, s46, 0x16000
	s_addc_u32 s57, s47, 0
	global_store_dwordx4 v151, v[242:245], s[56:57] sc1
	s_add_u32 s56, s52, 0xb0000
	s_addc_u32 s57, s53, 0
	global_store_dwordx4 v150, v[48:51], s[56:57]
	global_store_dwordx4 v150, v[52:55], s[56:57] offset:16
	s_add_u32 s56, s52, 0xb5800
	s_addc_u32 s57, s53, 0
	global_store_dwordx4 v150, v[120:123], s[56:57]
	global_store_dwordx4 v150, v[88:91], s[56:57] offset:16
	s_add_u32 s56, s52, 0xb2c00
	s_addc_u32 s57, s53, 0
	global_store_dwordx4 v150, v[56:59], s[56:57]
	global_store_dwordx4 v150, v[60:63], s[56:57] offset:16
	s_add_u32 s56, s52, 0xb8400
	s_addc_u32 s57, s53, 0
	global_store_dwordx4 v150, v[104:107], s[56:57]
	global_store_dwordx4 v150, v[72:75], s[56:57] offset:16
	s_add_u32 s14, s20, 0x210000
	s_addc_u32 s15, s21, 0
	global_load_dwordx4 v[32:35], v150, s[14:15]
	global_load_dwordx4 v[36:39], v150, s[14:15] offset:16
	s_add_u32 s56, s14, 0x2c00
	s_addc_u32 s57, s15, 0
	global_load_dwordx4 v[40:43], v150, s[56:57]
	global_load_dwordx4 v[44:47], v150, s[56:57] offset:16
	s_add_u32 s56, s14, 0x5800
	s_addc_u32 s57, s15, 0
	global_load_dwordx4 v[48:51], v150, s[56:57]
	global_load_dwordx4 v[52:55], v150, s[56:57] offset:16
	s_add_u32 s56, s14, 0x8400
	s_addc_u32 s57, s15, 0
	global_load_dwordx4 v[56:59], v150, s[56:57]
	global_load_dwordx4 v[60:63], v150, s[56:57] offset:16
	s_waitcnt vmcnt(17)
; __device__ __forceinline__ f32x2 gelu_pk(f32x2 v) {
;     const f32x2 av = __builtin_elementwise_abs(v), d = av * 0.2316418882f + 1.0f;
;     f32x2 t; t.x = __builtin_amdgcn_rcpf(d.x); t.y = __builtin_amdgcn_rcpf(d.y);
;     __device__ __forceinline__ void operator()(const f32x4 (&acc)[2][2][4][2], const Unit& u, int wr, int wc, int fr, int fq) const {
;     ...
;                     for (int m = 0; m < 4; ++m) {
;                         f32x4 cv;
;                         if (!samp) {
;                             const f32x4 prev = m ? v[m - 1] : hv;
; #pragma unroll
;                             for (int e = 0; e < 4; ++e) {
;                                 const int vi = __float_as_int(v[m][e]), pi = __float_as_int(prev[e]);
;                                 const int o1 = __builtin_amdgcn_mov_dpp(pi, 0x121, 0xf, 0xf, false);
;                                 const int o2 = __builtin_amdgcn_mov_dpp(pi, 0x122, 0xf, 0xf, false);
;                                 const float p1 = __int_as_float(__builtin_amdgcn_update_dpp(o1, vi, 0x111, 0xf, 0xf, false));
;                                 const float p2 = __int_as_float(__builtin_amdgcn_update_dpp(o2, vi, 0x112, 0xf, 0xf, false));
;                                 cv[e] = cb[e] + cw0[e] * p2 + cw1[e] * p1 + cw2[e] * v[m][e];
;                             }
;                         } else {
;                             const int ns = rowb + 16 * m + fr - MP;
;                             f32x4 s0 = (f32x4){0.f, 0.f, 0.f, 0.f}, s1 = s0;
;                             if (ns < NS) {
;                                 s0 = *(const f32x4*)(state + (size_t)(ns * 2 + 0) * FF2 + oc); s1 = *(const f32x4*)(state + (size_t)(ns * 2 + 1) * FF2 + oc);
;                                 *(f32x4*)(ncs + (size_t)(ns * 2 + 0) * FF2 + oc) = s1; *(f32x4*)(ncs + (size_t)(ns * 2 + 1) * FF2 + oc) = v[m];
;                             }
;                             cv = cb + cw0 * s0 + cw1 * s1 + cw2 * v[m];
;                         }
;                         if (bj == 0) cg[m] = gelu4(cv);
;                         else {
;                             const f32x4 r = cg[m] * cv;
;                             v2u w; w.x = cvt_pk_bf16(r[0], r[1]); w.y = cvt_pk_bf16(r[2], r[3]);
;                             *(v2u*)(ACT + (size_t)(rowb + 16 * m + fr) * FF + 128 * u.pn + 32 * wc + 8 * fq + 4 * n) = w;
;                         }
	v_pk_fma_f32 v[254:255], v[170:171], v[0:1], v[132:133]
	v_pk_fma_f32 v[148:149], v[172:173], v[2:3], v[134:135]
	v_pk_fma_f32 v[254:255], v[186:187], v[16:17], v[254:255]
	v_pk_fma_f32 v[148:149], v[188:189], v[18:19], v[148:149]
	v_pk_fma_f32 v[254:255], v[202:203], v[116:117], v[254:255]
	v_pk_fma_f32 v[148:149], v[204:205], v[118:119], v[148:149]
	v_fma_f32 v246, |v254|, s38, 1.0
	v_fma_f32 v247, |v255|, s38, 1.0
	v_fma_f32 v248, |v148|, s38, 1.0
	v_fma_f32 v249, |v149|, s38, 1.0
	v_mul_f32_e32 v250, v254, v254
	v_mul_f32_e32 v251, v255, v255
	v_mul_f32_e32 v252, v148, v148
	v_mul_f32_e32 v253, v149, v149
	v_rcp_f32_e32 v246, v246
	v_rcp_f32_e32 v247, v247
	v_rcp_f32_e32 v248, v248
	v_rcp_f32_e32 v249, v249
	v_mul_f32_e32 v250, s72, v250
	v_mul_f32_e32 v251, s72, v251
	v_mul_f32_e32 v252, s72, v252
	v_mul_f32_e32 v253, s72, v253
	v_exp_f32_e32 v250, v250
	v_exp_f32_e32 v251, v251
	v_exp_f32_e32 v252, v252
	v_exp_f32_e32 v253, v253
	v_fmamk_f32 v238, v246, 0x3f07dc22, v219
	v_fmamk_f32 v239, v247, 0x3f07dc22, v219
	v_fmamk_f32 v240, v248, 0x3f07dc22, v219
	v_fmamk_f32 v241, v249, 0x3f07dc22, v219
	v_fma_f32 v238, v246, v238, s66
	v_fma_f32 v239, v247, v239, s66
	v_fma_f32 v240, v248, v240, s66
	v_fma_f32 v241, v249, v241, s66
	v_fma_f32 v238, v246, v238, s68
	v_fma_f32 v239, v247, v239, s68
	v_fma_f32 v240, v248, v240, s68
	v_fma_f32 v241, v249, v241, s68
	v_fma_f32 v238, v246, v238, s70
	v_fma_f32 v239, v247, v239, s70
	v_fma_f32 v240, v248, v240, s70
	v_fma_f32 v241, v249, v241, s70
	v_mul_f32_e32 v238, v246, v238
	v_mul_f32_e32 v239, v247, v239
	v_mul_f32_e32 v240, v248, v240
	v_mul_f32_e32 v241, v249, v241
	v_mul_f32_e32 v238, v250, v238
	v_mul_f32_e32 v239, v251, v239
	v_mul_f32_e32 v240, v252, v240
	v_mul_f32_e32 v241, v253, v241
	v_max_f32_e32 v246, 0, v254
	v_max_f32_e32 v247, 0, v255
	v_max_f32_e32 v248, 0, v148
	v_max_f32_e32 v249, 0, v149
	v_fma_f32 v238, -|v254|, v238, v246
	v_fma_f32 v239, -|v255|, v239, v247
	v_fma_f32 v240, -|v148|, v240, v248
	v_fma_f32 v241, -|v149|, v241, v249
	v_pk_fma_f32 v[254:255], v[178:179], v[8:9], v[140:141]
	v_pk_fma_f32 v[148:149], v[180:181], v[10:11], v[142:143]
	v_pk_fma_f32 v[254:255], v[194:195], v[24:25], v[254:255]
	v_pk_fma_f32 v[148:149], v[196:197], v[26:27], v[148:149]
	v_pk_fma_f32 v[254:255], v[210:211], v[100:101], v[254:255]
	v_pk_fma_f32 v[148:149], v[212:213], v[102:103], v[148:149]
	v_pk_mul_f32 v[254:255], v[238:239], v[254:255]
	v_pk_mul_f32 v[148:149], v[240:241], v[148:149]
	v_cvt_pk_bf16_f32 v242, v254, v255
	v_cvt_pk_bf16_f32 v243, v148, v149
	v_pk_fma_f32 v[254:255], v[174:175], v[4:5], v[136:137]
	v_pk_fma_f32 v[148:149], v[176:177], v[6:7], v[138:139]
	v_pk_fma_f32 v[254:255], v[190:191], v[20:21], v[254:255]
	v_pk_fma_f32 v[148:149], v[192:193], v[22:23], v[148:149]
	v_pk_fma_f32 v[254:255], v[206:207], v[84:85], v[254:255]
	v_pk_fma_f32 v[148:149], v[208:209], v[86:87], v[148:149]
	v_fma_f32 v246, |v254|, s38, 1.0
	v_fma_f32 v247, |v255|, s38, 1.0
	v_fma_f32 v248, |v148|, s38, 1.0
	v_fma_f32 v249, |v149|, s38, 1.0
	v_mul_f32_e32 v250, v254, v254
	v_mul_f32_e32 v251, v255, v255
	v_mul_f32_e32 v252, v148, v148
	v_mul_f32_e32 v253, v149, v149
	v_rcp_f32_e32 v246, v246
	v_rcp_f32_e32 v247, v247
	v_rcp_f32_e32 v248, v248
	v_rcp_f32_e32 v249, v249
	v_mul_f32_e32 v250, s72, v250
	v_mul_f32_e32 v251, s72, v251
	v_mul_f32_e32 v252, s72, v252
	v_mul_f32_e32 v253, s72, v253
	v_exp_f32_e32 v250, v250
	v_exp_f32_e32 v251, v251
	v_exp_f32_e32 v252, v252
	v_exp_f32_e32 v253, v253
	v_fmamk_f32 v238, v246, 0x3f07dc22, v219
	v_fmamk_f32 v239, v247, 0x3f07dc22, v219
	v_fmamk_f32 v240, v248, 0x3f07dc22, v219
	v_fmamk_f32 v241, v249, 0x3f07dc22, v219
	v_fma_f32 v238, v246, v238, s66
	v_fma_f32 v239, v247, v239, s66
	v_fma_f32 v240, v248, v240, s66
	v_fma_f32 v241, v249, v241, s66
	v_fma_f32 v238, v246, v238, s68
	v_fma_f32 v239, v247, v239, s68
	v_fma_f32 v240, v248, v240, s68
	v_fma_f32 v241, v249, v241, s68
	v_fma_f32 v238, v246, v238, s70
	v_fma_f32 v239, v247, v239, s70
	v_fma_f32 v240, v248, v240, s70
	v_fma_f32 v241, v249, v241, s70
	v_mul_f32_e32 v238, v246, v238
	v_mul_f32_e32 v239, v247, v239
	v_mul_f32_e32 v240, v248, v240
	v_mul_f32_e32 v241, v249, v241
	v_mul_f32_e32 v238, v250, v238
	v_mul_f32_e32 v239, v251, v239
	v_mul_f32_e32 v240, v252, v240
	v_mul_f32_e32 v241, v253, v241
	v_max_f32_e32 v246, 0, v254
	v_max_f32_e32 v247, 0, v255
	v_max_f32_e32 v248, 0, v148
	v_max_f32_e32 v249, 0, v149
	v_fma_f32 v238, -|v254|, v238, v246
	v_fma_f32 v239, -|v255|, v239, v247
	v_fma_f32 v240, -|v148|, v240, v248
	v_fma_f32 v241, -|v149|, v241, v249
	v_pk_fma_f32 v[254:255], v[182:183], v[12:13], v[144:145]
	v_pk_fma_f32 v[148:149], v[184:185], v[14:15], v[146:147]
	v_pk_fma_f32 v[254:255], v[198:199], v[28:29], v[254:255]
	v_pk_fma_f32 v[148:149], v[200:201], v[30:31], v[148:149]
	v_pk_fma_f32 v[254:255], v[128:129], v[68:69], v[254:255]
	v_pk_fma_f32 v[148:149], v[130:131], v[70:71], v[148:149]
	v_pk_mul_f32 v[254:255], v[238:239], v[254:255]
	v_pk_mul_f32 v[148:149], v[240:241], v[148:149]
	v_cvt_pk_bf16_f32 v244, v254, v255
	v_cvt_pk_bf16_f32 v245, v148, v149
	s_add_u32 s56, s46, 0x2c000
	s_addc_u32 s57, s47, 0
	global_store_dwordx4 v151, v[242:245], s[56:57] sc1
	s_add_u32 s56, s52, 0x160000
	s_addc_u32 s57, s53, 0
	global_store_dwordx4 v150, v[16:19], s[56:57]
	global_store_dwordx4 v150, v[20:23], s[56:57] offset:16
	s_add_u32 s56, s52, 0x165800
	s_addc_u32 s57, s53, 0
	global_store_dwordx4 v150, v[116:119], s[56:57]
	global_store_dwordx4 v150, v[84:87], s[56:57] offset:16
	s_add_u32 s56, s52, 0x162c00
	s_addc_u32 s57, s53, 0
	global_store_dwordx4 v150, v[24:27], s[56:57]
	global_store_dwordx4 v150, v[28:31], s[56:57] offset:16
	s_add_u32 s56, s52, 0x168400
	s_addc_u32 s57, s53, 0
	global_store_dwordx4 v150, v[100:103], s[56:57]
	global_store_dwordx4 v150, v[68:71], s[56:57] offset:16
	s_waitcnt vmcnt(9)
; __device__ __forceinline__ f32x2 gelu_pk(f32x2 v) {
;     const f32x2 av = __builtin_elementwise_abs(v), d = av * 0.2316418882f + 1.0f;
;     f32x2 t; t.x = __builtin_amdgcn_rcpf(d.x); t.y = __builtin_amdgcn_rcpf(d.y);
;     __device__ __forceinline__ void operator()(const f32x4 (&acc)[2][2][4][2], const Unit& u, int wr, int wc, int fr, int fq) const {
;     ...
;                     for (int m = 0; m < 4; ++m) {
;                         f32x4 cv;
;                         if (!samp) {
;                             const f32x4 prev = m ? v[m - 1] : hv;
; #pragma unroll
;                             for (int e = 0; e < 4; ++e) {
;                                 const int vi = __float_as_int(v[m][e]), pi = __float_as_int(prev[e]);
;                                 const int o1 = __builtin_amdgcn_mov_dpp(pi, 0x121, 0xf, 0xf, false);
;                                 const int o2 = __builtin_amdgcn_mov_dpp(pi, 0x122, 0xf, 0xf, false);
;                                 const float p1 = __int_as_float(__builtin_amdgcn_update_dpp(o1, vi, 0x111, 0xf, 0xf, false));
;                                 const float p2 = __int_as_float(__builtin_amdgcn_update_dpp(o2, vi, 0x112, 0xf, 0xf, false));
;                                 cv[e] = cb[e] + cw0[e] * p2 + cw1[e] * p1 + cw2[e] * v[m][e];
;                             }
;                         } else {
;                             const int ns = rowb + 16 * m + fr - MP;
;                             f32x4 s0 = (f32x4){0.f, 0.f, 0.f, 0.f}, s1 = s0;
;                             if (ns < NS) {
;                                 s0 = *(const f32x4*)(state + (size_t)(ns * 2 + 0) * FF2 + oc); s1 = *(const f32x4*)(state + (size_t)(ns * 2 + 1) * FF2 + oc);
;                                 *(f32x4*)(ncs + (size_t)(ns * 2 + 0) * FF2 + oc) = s1; *(f32x4*)(ncs + (size_t)(ns * 2 + 1) * FF2 + oc) = v[m];
;                             }
;                             cv = cb + cw0 * s0 + cw1 * s1 + cw2 * v[m];
;                         }
;                         if (bj == 0) cg[m] = gelu4(cv);
;                         else {
;                             const f32x4 r = cg[m] * cv;
;                             v2u w; w.x = cvt_pk_bf16(r[0], r[1]); w.y = cvt_pk_bf16(r[2], r[3]);
;                             *(v2u*)(ACT + (size_t)(rowb + 16 * m + fr) * FF + 128 * u.pn + 32 * wc + 8 * fq + 4 * n) = w;
;                         }
	v_pk_fma_f32 v[254:255], v[170:171], v[32:33], v[132:133]
	v_pk_fma_f32 v[148:149], v[172:173], v[34:35], v[134:135]
	v_pk_fma_f32 v[254:255], v[186:187], v[48:49], v[254:255]
	v_pk_fma_f32 v[148:149], v[188:189], v[50:51], v[148:149]
	v_pk_fma_f32 v[254:255], v[202:203], v[112:113], v[254:255]
	v_pk_fma_f32 v[148:149], v[204:205], v[114:115], v[148:149]
	v_fma_f32 v246, |v254|, s38, 1.0
	v_fma_f32 v247, |v255|, s38, 1.0
	v_fma_f32 v248, |v148|, s38, 1.0
	v_fma_f32 v249, |v149|, s38, 1.0
	v_mul_f32_e32 v250, v254, v254
	v_mul_f32_e32 v251, v255, v255
	v_mul_f32_e32 v252, v148, v148
	v_mul_f32_e32 v253, v149, v149
	v_rcp_f32_e32 v246, v246
	v_rcp_f32_e32 v247, v247
	v_rcp_f32_e32 v248, v248
	v_rcp_f32_e32 v249, v249
	v_mul_f32_e32 v250, s72, v250
	v_mul_f32_e32 v251, s72, v251
	v_mul_f32_e32 v252, s72, v252
	v_mul_f32_e32 v253, s72, v253
	v_exp_f32_e32 v250, v250
	v_exp_f32_e32 v251, v251
	v_exp_f32_e32 v252, v252
	v_exp_f32_e32 v253, v253
	v_fmamk_f32 v238, v246, 0x3f07dc22, v219
	v_fmamk_f32 v239, v247, 0x3f07dc22, v219
	v_fmamk_f32 v240, v248, 0x3f07dc22, v219
	v_fmamk_f32 v241, v249, 0x3f07dc22, v219
	v_fma_f32 v238, v246, v238, s66
	v_fma_f32 v239, v247, v239, s66
	v_fma_f32 v240, v248, v240, s66
	v_fma_f32 v241, v249, v241, s66
	v_fma_f32 v238, v246, v238, s68
	v_fma_f32 v239, v247, v239, s68
	v_fma_f32 v240, v248, v240, s68
	v_fma_f32 v241, v249, v241, s68
	v_fma_f32 v238, v246, v238, s70
	v_fma_f32 v239, v247, v239, s70
	v_fma_f32 v240, v248, v240, s70
	v_fma_f32 v241, v249, v241, s70
	v_mul_f32_e32 v238, v246, v238
	v_mul_f32_e32 v239, v247, v239
	v_mul_f32_e32 v240, v248, v240
	v_mul_f32_e32 v241, v249, v241
	v_mul_f32_e32 v238, v250, v238
	v_mul_f32_e32 v239, v251, v239
	v_mul_f32_e32 v240, v252, v240
	v_mul_f32_e32 v241, v253, v241
	v_max_f32_e32 v246, 0, v254
	v_max_f32_e32 v247, 0, v255
	v_max_f32_e32 v248, 0, v148
	v_max_f32_e32 v249, 0, v149
	v_fma_f32 v238, -|v254|, v238, v246
	v_fma_f32 v239, -|v255|, v239, v247
	v_fma_f32 v240, -|v148|, v240, v248
	v_fma_f32 v241, -|v149|, v241, v249
	v_pk_fma_f32 v[254:255], v[178:179], v[40:41], v[140:141]
	v_pk_fma_f32 v[148:149], v[180:181], v[42:43], v[142:143]
	v_pk_fma_f32 v[254:255], v[194:195], v[56:57], v[254:255]
	v_pk_fma_f32 v[148:149], v[196:197], v[58:59], v[148:149]
	v_pk_fma_f32 v[254:255], v[210:211], v[96:97], v[254:255]
	v_pk_fma_f32 v[148:149], v[212:213], v[98:99], v[148:149]
	v_pk_mul_f32 v[254:255], v[238:239], v[254:255]
	v_pk_mul_f32 v[148:149], v[240:241], v[148:149]
	v_cvt_pk_bf16_f32 v242, v254, v255
	v_cvt_pk_bf16_f32 v243, v148, v149
	v_pk_fma_f32 v[254:255], v[174:175], v[36:37], v[136:137]
	v_pk_fma_f32 v[148:149], v[176:177], v[38:39], v[138:139]
	v_pk_fma_f32 v[254:255], v[190:191], v[52:53], v[254:255]
	v_pk_fma_f32 v[148:149], v[192:193], v[54:55], v[148:149]
	v_pk_fma_f32 v[254:255], v[206:207], v[80:81], v[254:255]
	v_pk_fma_f32 v[148:149], v[208:209], v[82:83], v[148:149]
	v_fma_f32 v246, |v254|, s38, 1.0
	v_fma_f32 v247, |v255|, s38, 1.0
	v_fma_f32 v248, |v148|, s38, 1.0
	v_fma_f32 v249, |v149|, s38, 1.0
	v_mul_f32_e32 v250, v254, v254
	v_mul_f32_e32 v251, v255, v255
	v_mul_f32_e32 v252, v148, v148
	v_mul_f32_e32 v253, v149, v149
	v_rcp_f32_e32 v246, v246
	v_rcp_f32_e32 v247, v247
	v_rcp_f32_e32 v248, v248
	v_rcp_f32_e32 v249, v249
	v_mul_f32_e32 v250, s72, v250
	v_mul_f32_e32 v251, s72, v251
	v_mul_f32_e32 v252, s72, v252
	v_mul_f32_e32 v253, s72, v253
	v_exp_f32_e32 v250, v250
	v_exp_f32_e32 v251, v251
	v_exp_f32_e32 v252, v252
	v_exp_f32_e32 v253, v253
	v_fmamk_f32 v238, v246, 0x3f07dc22, v219
	v_fmamk_f32 v239, v247, 0x3f07dc22, v219
	v_fmamk_f32 v240, v248, 0x3f07dc22, v219
	v_fmamk_f32 v241, v249, 0x3f07dc22, v219
	v_fma_f32 v238, v246, v238, s66
	v_fma_f32 v239, v247, v239, s66
	v_fma_f32 v240, v248, v240, s66
	v_fma_f32 v241, v249, v241, s66
	v_fma_f32 v238, v246, v238, s68
	v_fma_f32 v239, v247, v239, s68
	v_fma_f32 v240, v248, v240, s68
	v_fma_f32 v241, v249, v241, s68
	v_fma_f32 v238, v246, v238, s70
	v_fma_f32 v239, v247, v239, s70
	v_fma_f32 v240, v248, v240, s70
	v_fma_f32 v241, v249, v241, s70
	v_mul_f32_e32 v238, v246, v238
	v_mul_f32_e32 v239, v247, v239
	v_mul_f32_e32 v240, v248, v240
	v_mul_f32_e32 v241, v249, v241
	v_mul_f32_e32 v238, v250, v238
	v_mul_f32_e32 v239, v251, v239
	v_mul_f32_e32 v240, v252, v240
	v_mul_f32_e32 v241, v253, v241
	v_max_f32_e32 v246, 0, v254
	v_max_f32_e32 v247, 0, v255
	v_max_f32_e32 v248, 0, v148
	v_max_f32_e32 v249, 0, v149
	v_fma_f32 v238, -|v254|, v238, v246
	v_fma_f32 v239, -|v255|, v239, v247
	v_fma_f32 v240, -|v148|, v240, v248
	v_fma_f32 v241, -|v149|, v241, v249
	v_pk_fma_f32 v[254:255], v[182:183], v[44:45], v[144:145]
	v_pk_fma_f32 v[148:149], v[184:185], v[46:47], v[146:147]
	v_pk_fma_f32 v[254:255], v[198:199], v[60:61], v[254:255]
	v_pk_fma_f32 v[148:149], v[200:201], v[62:63], v[148:149]
	v_pk_fma_f32 v[254:255], v[128:129], v[64:65], v[254:255]
	v_pk_fma_f32 v[148:149], v[130:131], v[66:67], v[148:149]
	v_pk_mul_f32 v[254:255], v[238:239], v[254:255]
	v_pk_mul_f32 v[148:149], v[240:241], v[148:149]
	v_cvt_pk_bf16_f32 v244, v254, v255
	v_cvt_pk_bf16_f32 v245, v148, v149
	s_add_u32 s56, s46, 0x42000
	s_addc_u32 s57, s47, 0
	global_store_dwordx4 v151, v[242:245], s[56:57] sc1
	s_add_u32 s56, s52, 0x210000
	s_addc_u32 s57, s53, 0
	global_store_dwordx4 v150, v[48:51], s[56:57]
	global_store_dwordx4 v150, v[52:55], s[56:57] offset:16
	s_add_u32 s56, s52, 0x215800
	s_addc_u32 s57, s53, 0
	global_store_dwordx4 v150, v[112:115], s[56:57]
	global_store_dwordx4 v150, v[80:83], s[56:57] offset:16
	s_add_u32 s56, s52, 0x212c00
	s_addc_u32 s57, s53, 0
	global_store_dwordx4 v150, v[56:59], s[56:57]
	global_store_dwordx4 v150, v[60:63], s[56:57] offset:16
	s_add_u32 s56, s52, 0x218400
	s_addc_u32 s57, s53, 0
	global_store_dwordx4 v150, v[96:99], s[56:57]
	global_store_dwordx4 v150, v[64:67], s[56:57] offset:16
	v_readlane_b32 s90, v236, 23
	v_readlane_b32 s91, v236, 24
	s_nop 3
	s_branch .Lfs_done
